# big-GEMM K-loops: duplicate lgkmcnt(0) after the pre-MFMA barrier removed (the identical wait sits right before the barrier), with both setprio moves
# baseline (speedup 1.0000x reference)
; #define PG8_STAGE(bufoff, gbase, voff) do { _Pragma("unroll") for (int _i = 0; _i < 2; ++_i) \
;         __builtin_amdgcn_global_load_lds((const unsigned*)((const char*)(gbase) + (voff)[_i]), (PG8_LAS unsigned*)(lds + (bufoff) + ldsw + _i * 8192), 16, 0, 0); } while (0)
; #define PG8_LDA(dst, b, h) do { _Pragma("unroll") for (int m = 0; m < 4; ++m) _Pragma("unroll") for (int k = 0; k < 2; ++k) dst[m][k] = *(const PG8_LAS bf16x8*)(lds + PG8_SA(b, h) + aoff + m * 2048 + k * 1024); } while (0)
; #define PG8_LDB(dst, b, h) do { _Pragma("unroll") for (int n = 0; n < 2; ++n) _Pragma("unroll") for (int k = 0; k < 2; ++k) dst[n][k] = *(const PG8_LAS bf16x8*)(lds + PG8_SB(b, h) + boff + n * 2048 + k * 1024); } while (0)
; #define PG8_MMA(ai, bj, At, Bt) do { __builtin_amdgcn_s_setprio(1); _Pragma("unroll") for (int m = 0; m < 4; ++m) _Pragma("unroll") for (int n = 0; n < 2; ++n) _Pragma("unroll") for (int k = 0; k < 2; ++k) \
;         acc[ai][bj][m][n] = __builtin_amdgcn_mfma_f32_16x16x32_bf16(Bt[n][k], At[m][k], acc[ai][bj][m][n], 0, 0, 0); __builtin_amdgcn_s_setprio(0); } while (0)
; #define PG8_WAIT_V(n) asm volatile("s_waitcnt vmcnt(" #n ")" ::: "memory")
; #define PG8_WAIT_L(n) asm volatile("s_waitcnt lgkmcnt(" #n ")" ::: "memory")
; #define PG8_BAR __builtin_amdgcn_s_barrier()
; #define PG8_SCHED __builtin_amdgcn_sched_barrier(0)
; template <class Epi, class Sched, bool ALIGN_EPI = false, bool SP2 = false>
; __device__ __forceinline__ void gemm_phase(PG8_LAS unsigned char* lds, const Gemm g, const Sched& S, const Epi& E) {
;     ...
;             const char* a2 = last ? nA : cA + (size_t)(t + 2) * kstep; const char* b2 = last ? nB : cB + (size_t)(t + 2) * kstep;
;             const char* a3 = a2 + kstep; const char* b3 = b2 + kstep;
;             if (last && has_next) S.a_ready(nxt);
;             if constexpr (SP2) {
;             PG8_LDB(B0, 0, 0); PG8_LDB(B1, 0, 1); PG8_SCHED; PG8_LDA(At, 0, 0); PG8_STAGE(PG8_SA(1, 1), a1 + hstep, voffA);
;             PG8_WAIT_V(8); PG8_WAIT_L(0); PG8_BAR; PG8_MMA(0, 0, At, B0); PG8_MMA(0, 1, At, B1); PG8_BAR; PG8_SCHED;
;             PG8_LDA(At, 0, 1); PG8_STAGE(PG8_SB(0, 0), b2, voffB); PG8_STAGE(PG8_SB(0, 1), b2 + hstep, voffB); PG8_STAGE(PG8_SA(0, 0), a2, voffA);
;             PG8_WAIT_V(8); PG8_WAIT_L(0); PG8_BAR; PG8_MMA(1, 0, At, B0); PG8_MMA(1, 1, At, B1); PG8_BAR; PG8_SCHED;
.LBB0_253:
	ds_read_b128 v[148:151], v161
	ds_read_b128 v[166:169], v161 offset:1024
	ds_read_b128 v[170:173], v161 offset:2048
	ds_read_b128 v[174:177], v161 offset:3072
	ds_read_b128 v[178:181], v162
	ds_read_b128 v[184:187], v162 offset:1024
	ds_read_b128 v[188:191], v162 offset:2048
	ds_read_b128 v[192:195], v162 offset:3072
	s_add_u32 s30, s28, 0xfff80080
	s_addc_u32 s31, s29, -1
	s_cmp_eq_u32 s56, 28
	s_cselect_b32 s35, s3, s31
	s_cselect_b32 s34, s21, s30
	s_cselect_b32 s31, s19, s55
	s_cselect_b32 s30, s27, s54
	v_lshl_add_u64 v[152:153], s[28:29], 0, v[140:141]
	s_add_i32 m0, s38, 0xc000
	ds_read_b128 v[196:199], v163
	ds_read_b128 v[200:203], v163 offset:1024
	ds_read_b128 v[204:207], v163 offset:2048
	ds_read_b128 v[208:211], v163 offset:3072
	ds_read_b128 v[212:215], v163 offset:4096
	ds_read_b128 v[216:219], v163 offset:5120
	ds_read_b128 v[220:223], v163 offset:6144
	ds_read_b128 v[224:227], v163 offset:7168
	global_load_lds_dwordx4 v[152:153], off
	v_lshl_add_u64 v[152:153], s[28:29], 0, v[142:143]
	s_add_i32 m0, s38, 0xe000
	s_nop 0
	global_load_lds_dwordx4 v[152:153], off
	s_waitcnt vmcnt(8)
	s_waitcnt lgkmcnt(0)
	s_setprio 1
	s_barrier
	v_mfma_f32_16x16x32_bf16 v[124:127], v[148:151], v[196:199], v[124:127]
	v_mfma_f32_16x16x32_bf16 v[120:123], v[170:173], v[196:199], v[120:123]
	v_mfma_f32_16x16x32_bf16 v[116:119], v[148:151], v[204:207], v[116:119]
	v_mfma_f32_16x16x32_bf16 v[112:115], v[170:173], v[204:207], v[112:115]
	v_mfma_f32_16x16x32_bf16 v[108:111], v[148:151], v[212:215], v[108:111]
	v_mfma_f32_16x16x32_bf16 v[104:107], v[170:173], v[212:215], v[104:107]
	v_mfma_f32_16x16x32_bf16 v[100:103], v[148:151], v[220:223], v[100:103]
	v_mfma_f32_16x16x32_bf16 v[96:99], v[170:173], v[220:223], v[96:99]
	v_mfma_f32_16x16x32_bf16 v[124:127], v[166:169], v[200:203], v[124:127]
	v_mfma_f32_16x16x32_bf16 v[120:123], v[174:177], v[200:203], v[120:123]
	v_mfma_f32_16x16x32_bf16 v[116:119], v[166:169], v[208:211], v[116:119]
	v_mfma_f32_16x16x32_bf16 v[112:115], v[174:177], v[208:211], v[112:115]
	v_mfma_f32_16x16x32_bf16 v[108:111], v[166:169], v[216:219], v[108:111]
	v_mfma_f32_16x16x32_bf16 v[104:107], v[174:177], v[216:219], v[104:107]
	v_mfma_f32_16x16x32_bf16 v[100:103], v[166:169], v[224:227], v[100:103]
	v_mfma_f32_16x16x32_bf16 v[96:99], v[174:177], v[224:227], v[96:99]
	s_setprio 0
	s_setprio 1
	v_mfma_f32_16x16x32_bf16 v[92:95], v[178:181], v[196:199], v[92:95]
	v_mfma_f32_16x16x32_bf16 v[88:91], v[188:191], v[196:199], v[88:91]
	v_mfma_f32_16x16x32_bf16 v[84:87], v[178:181], v[204:207], v[84:87]
	v_mfma_f32_16x16x32_bf16 v[80:83], v[188:191], v[204:207], v[80:83]
	v_mfma_f32_16x16x32_bf16 v[76:79], v[178:181], v[212:215], v[76:79]
	v_mfma_f32_16x16x32_bf16 v[72:75], v[188:191], v[212:215], v[72:75]
	v_mfma_f32_16x16x32_bf16 v[68:71], v[178:181], v[220:223], v[68:71]
	v_mfma_f32_16x16x32_bf16 v[64:67], v[188:191], v[220:223], v[64:67]
	v_mfma_f32_16x16x32_bf16 v[92:95], v[184:187], v[200:203], v[92:95]
	v_mfma_f32_16x16x32_bf16 v[88:91], v[192:195], v[200:203], v[88:91]
	v_mfma_f32_16x16x32_bf16 v[84:87], v[184:187], v[208:211], v[84:87]
	v_mfma_f32_16x16x32_bf16 v[80:83], v[192:195], v[208:211], v[80:83]
	v_mfma_f32_16x16x32_bf16 v[76:79], v[184:187], v[216:219], v[76:79]
	v_mfma_f32_16x16x32_bf16 v[72:75], v[192:195], v[216:219], v[72:75]
	v_mfma_f32_16x16x32_bf16 v[68:71], v[184:187], v[224:227], v[68:71]
	v_mfma_f32_16x16x32_bf16 v[64:67], v[192:195], v[224:227], v[64:67]
	s_barrier
	s_setprio 0
	s_add_i32 s57, s48, s37
	v_lshl_add_u64 v[152:153], s[30:31], 0, v[130:131]
	s_mov_b32 m0, s57
	ds_read_b128 v[196:199], v163 offset:16384
	ds_read_b128 v[200:203], v163 offset:17408
	ds_read_b128 v[204:207], v163 offset:18432
	ds_read_b128 v[208:211], v163 offset:19456
	ds_read_b128 v[212:215], v163 offset:20480
	ds_read_b128 v[216:219], v163 offset:21504
	ds_read_b128 v[220:223], v163 offset:22528
	ds_read_b128 v[224:227], v163 offset:23552
	global_load_lds_dwordx4 v[152:153], off
	s_add_i32 m0, s57, 0x2000
	s_add_u32 s58, s30, 0x80000
	v_lshl_add_u64 v[228:229], s[30:31], 0, v[134:135]
	s_addc_u32 s59, s31, 0
	s_add_i32 s57, s49, s37
	global_load_lds_dwordx4 v[228:229], off
	v_lshl_add_u64 v[230:231], s[58:59], 0, v[130:131]
	s_mov_b32 m0, s57
	v_lshl_add_u64 v[232:233], s[34:35], 0, v[132:133]
	global_load_lds_dwordx4 v[230:231], off
	v_lshl_add_u64 v[230:231], s[58:59], 0, v[134:135]
	s_add_i32 m0, s57, 0x2000
	s_nop 0
	global_load_lds_dwordx4 v[230:231], off
	v_lshl_add_u64 v[230:231], s[34:35], 0, v[128:129]
	s_mov_b32 m0, s38
	s_nop 0
	global_load_lds_dwordx4 v[230:231], off
	s_mov_b32 m0, s39
	s_nop 0
	global_load_lds_dwordx4 v[232:233], off
	s_waitcnt vmcnt(8)
	s_waitcnt lgkmcnt(0)
	s_setprio 1
	s_barrier
; #define PG8_STAGE(bufoff, gbase, voff) do { _Pragma("unroll") for (int _i = 0; _i < 2; ++_i) \
;         __builtin_amdgcn_global_load_lds((const unsigned*)((const char*)(gbase) + (voff)[_i]), (PG8_LAS unsigned*)(lds + (bufoff) + ldsw + _i * 8192), 16, 0, 0); } while (0)
; #define PG8_LDA(dst, b, h) do { _Pragma("unroll") for (int m = 0; m < 4; ++m) _Pragma("unroll") for (int k = 0; k < 2; ++k) dst[m][k] = *(const PG8_LAS bf16x8*)(lds + PG8_SA(b, h) + aoff + m * 2048 + k * 1024); } while (0)
; #define PG8_LDB(dst, b, h) do { _Pragma("unroll") for (int n = 0; n < 2; ++n) _Pragma("unroll") for (int k = 0; k < 2; ++k) dst[n][k] = *(const PG8_LAS bf16x8*)(lds + PG8_SB(b, h) + boff + n * 2048 + k * 1024); } while (0)
; #define PG8_MMA(ai, bj, At, Bt) do { __builtin_amdgcn_s_setprio(1); _Pragma("unroll") for (int m = 0; m < 4; ++m) _Pragma("unroll") for (int n = 0; n < 2; ++n) _Pragma("unroll") for (int k = 0; k < 2; ++k) \
;         acc[ai][bj][m][n] = __builtin_amdgcn_mfma_f32_16x16x32_bf16(Bt[n][k], At[m][k], acc[ai][bj][m][n], 0, 0, 0); __builtin_amdgcn_s_setprio(0); } while (0)
; #define PG8_WAIT_V(n) asm volatile("s_waitcnt vmcnt(" #n ")" ::: "memory")
; #define PG8_WAIT_L(n) asm volatile("s_waitcnt lgkmcnt(" #n ")" ::: "memory")
; #define PG8_BAR __builtin_amdgcn_s_barrier()
; #define PG8_SCHED __builtin_amdgcn_sched_barrier(0)
; template <class Epi, class Sched, bool ALIGN_EPI = false, bool SP2 = false>
; __device__ __forceinline__ void gemm_phase(PG8_LAS unsigned char* lds, const Gemm g, const Sched& S, const Epi& E) {
;     ...
;             PG8_WAIT_V(8); PG8_WAIT_L(0); PG8_BAR; PG8_MMA(1, 0, At, B0); PG8_MMA(1, 1, At, B1); PG8_BAR; PG8_SCHED;
;             PG8_LDB(B0, 1, 0); PG8_LDB(B1, 1, 1); PG8_SCHED; PG8_LDA(At, 1, 0); PG8_STAGE(PG8_SA(0, 1), a2 + hstep, voffA);
;             PG8_WAIT_V(8); PG8_WAIT_L(0); PG8_BAR; PG8_MMA(0, 0, At, B0); PG8_MMA(0, 1, At, B1); PG8_BAR; PG8_SCHED;
	v_mfma_f32_16x16x32_bf16 v[60:63], v[148:151], v[196:199], v[60:63]
	v_mfma_f32_16x16x32_bf16 v[56:59], v[170:173], v[196:199], v[56:59]
	v_mfma_f32_16x16x32_bf16 v[52:55], v[148:151], v[204:207], v[52:55]
	v_mfma_f32_16x16x32_bf16 v[48:51], v[170:173], v[204:207], v[48:51]
	v_mfma_f32_16x16x32_bf16 v[44:47], v[148:151], v[212:215], v[44:47]
	v_mfma_f32_16x16x32_bf16 v[40:43], v[170:173], v[212:215], v[40:43]
	v_mfma_f32_16x16x32_bf16 v[36:39], v[148:151], v[220:223], v[36:39]
	v_mfma_f32_16x16x32_bf16 v[32:35], v[170:173], v[220:223], v[32:35]
	v_mfma_f32_16x16x32_bf16 v[60:63], v[166:169], v[200:203], v[60:63]
	v_mfma_f32_16x16x32_bf16 v[56:59], v[174:177], v[200:203], v[56:59]
	v_mfma_f32_16x16x32_bf16 v[52:55], v[166:169], v[208:211], v[52:55]
	v_mfma_f32_16x16x32_bf16 v[48:51], v[174:177], v[208:211], v[48:51]
	v_mfma_f32_16x16x32_bf16 v[44:47], v[166:169], v[216:219], v[44:47]
	v_mfma_f32_16x16x32_bf16 v[40:43], v[174:177], v[216:219], v[40:43]
	v_mfma_f32_16x16x32_bf16 v[36:39], v[166:169], v[224:227], v[36:39]
	v_mfma_f32_16x16x32_bf16 v[32:35], v[174:177], v[224:227], v[32:35]
	s_setprio 0
	s_setprio 1
	v_mfma_f32_16x16x32_bf16 v[28:31], v[178:181], v[196:199], v[28:31]
	v_mfma_f32_16x16x32_bf16 v[24:27], v[188:191], v[196:199], v[24:27]
	v_mfma_f32_16x16x32_bf16 v[20:23], v[178:181], v[204:207], v[20:23]
	v_mfma_f32_16x16x32_bf16 v[16:19], v[188:191], v[204:207], v[16:19]
	v_mfma_f32_16x16x32_bf16 v[12:15], v[178:181], v[212:215], v[12:15]
	v_mfma_f32_16x16x32_bf16 v[8:11], v[188:191], v[212:215], v[8:11]
	v_mfma_f32_16x16x32_bf16 v[4:7], v[178:181], v[220:223], v[4:7]
	v_mfma_f32_16x16x32_bf16 v[0:3], v[188:191], v[220:223], v[0:3]
	v_mfma_f32_16x16x32_bf16 v[28:31], v[184:187], v[200:203], v[28:31]
	v_mfma_f32_16x16x32_bf16 v[24:27], v[192:195], v[200:203], v[24:27]
	v_mfma_f32_16x16x32_bf16 v[20:23], v[184:187], v[208:211], v[20:23]
	v_mfma_f32_16x16x32_bf16 v[16:19], v[192:195], v[208:211], v[16:19]
	v_mfma_f32_16x16x32_bf16 v[12:15], v[184:187], v[216:219], v[12:15]
	v_mfma_f32_16x16x32_bf16 v[8:11], v[192:195], v[216:219], v[8:11]
	v_mfma_f32_16x16x32_bf16 v[4:7], v[184:187], v[224:227], v[4:7]
	v_mfma_f32_16x16x32_bf16 v[0:3], v[192:195], v[224:227], v[0:3]
	s_barrier
	s_setprio 0
	s_add_i32 s57, 0, 0x18000
	v_add_u32_e32 v136, s57, v159
	s_add_i32 s58, 0, 0x1c000
	ds_read_b128 v[148:151], v136
	ds_read_b128 v[166:169], v136 offset:1024
	ds_read_b128 v[170:173], v136 offset:2048
	ds_read_b128 v[174:177], v136 offset:3072
	v_add_u32_e32 v136, s58, v159
	ds_read_b128 v[178:181], v136
	ds_read_b128 v[184:187], v136 offset:1024
	ds_read_b128 v[188:191], v136 offset:2048
	ds_read_b128 v[192:195], v136 offset:3072
	s_add_u32 s34, s34, 0x80000
	s_addc_u32 s35, s35, 0
	s_mov_b32 m0, s40
	v_lshl_add_u64 v[234:235], s[34:35], 0, v[128:129]
	ds_read_b128 v[196:199], v163 offset:32768
	ds_read_b128 v[200:203], v163 offset:33792
	ds_read_b128 v[204:207], v163 offset:34816
	ds_read_b128 v[208:211], v163 offset:35840
	ds_read_b128 v[212:215], v163 offset:36864
	ds_read_b128 v[216:219], v163 offset:37888
	ds_read_b128 v[220:223], v163 offset:38912
	ds_read_b128 v[224:227], v163 offset:39936
	global_load_lds_dwordx4 v[234:235], off
	v_lshl_add_u64 v[234:235], s[34:35], 0, v[132:133]
	s_mov_b32 m0, s41
	s_nop 0
	global_load_lds_dwordx4 v[234:235], off
	s_waitcnt vmcnt(8)
	s_waitcnt lgkmcnt(0)
	s_setprio 1
	s_barrier
	v_mfma_f32_16x16x32_bf16 v[124:127], v[148:151], v[196:199], v[124:127]
	v_mfma_f32_16x16x32_bf16 v[120:123], v[170:173], v[196:199], v[120:123]
	v_mfma_f32_16x16x32_bf16 v[116:119], v[148:151], v[204:207], v[116:119]
	v_mfma_f32_16x16x32_bf16 v[112:115], v[170:173], v[204:207], v[112:115]
	v_mfma_f32_16x16x32_bf16 v[108:111], v[148:151], v[212:215], v[108:111]
	v_mfma_f32_16x16x32_bf16 v[104:107], v[170:173], v[212:215], v[104:107]
	v_mfma_f32_16x16x32_bf16 v[100:103], v[148:151], v[220:223], v[100:103]
	v_mfma_f32_16x16x32_bf16 v[96:99], v[170:173], v[220:223], v[96:99]
	v_mfma_f32_16x16x32_bf16 v[124:127], v[166:169], v[200:203], v[124:127]
	v_mfma_f32_16x16x32_bf16 v[120:123], v[174:177], v[200:203], v[120:123]
	v_mfma_f32_16x16x32_bf16 v[116:119], v[166:169], v[208:211], v[116:119]
	v_mfma_f32_16x16x32_bf16 v[112:115], v[174:177], v[208:211], v[112:115]
	v_mfma_f32_16x16x32_bf16 v[108:111], v[166:169], v[216:219], v[108:111]
	v_mfma_f32_16x16x32_bf16 v[104:107], v[174:177], v[216:219], v[104:107]
	v_mfma_f32_16x16x32_bf16 v[100:103], v[166:169], v[224:227], v[100:103]
	v_mfma_f32_16x16x32_bf16 v[96:99], v[174:177], v[224:227], v[96:99]
	s_setprio 0
	s_setprio 1
	v_mfma_f32_16x16x32_bf16 v[92:95], v[178:181], v[196:199], v[92:95]
	v_mfma_f32_16x16x32_bf16 v[88:91], v[188:191], v[196:199], v[88:91]
	v_mfma_f32_16x16x32_bf16 v[84:87], v[178:181], v[204:207], v[84:87]
	v_mfma_f32_16x16x32_bf16 v[80:83], v[188:191], v[204:207], v[80:83]
	v_mfma_f32_16x16x32_bf16 v[76:79], v[178:181], v[212:215], v[76:79]
	v_mfma_f32_16x16x32_bf16 v[72:75], v[188:191], v[212:215], v[72:75]
	v_mfma_f32_16x16x32_bf16 v[68:71], v[178:181], v[220:223], v[68:71]
	v_mfma_f32_16x16x32_bf16 v[64:67], v[188:191], v[220:223], v[64:67]
	v_mfma_f32_16x16x32_bf16 v[92:95], v[184:187], v[200:203], v[92:95]
	v_mfma_f32_16x16x32_bf16 v[88:91], v[192:195], v[200:203], v[88:91]
	v_mfma_f32_16x16x32_bf16 v[84:87], v[184:187], v[208:211], v[84:87]
	v_mfma_f32_16x16x32_bf16 v[80:83], v[192:195], v[208:211], v[80:83]
	v_mfma_f32_16x16x32_bf16 v[76:79], v[184:187], v[216:219], v[76:79]
	v_mfma_f32_16x16x32_bf16 v[72:75], v[192:195], v[216:219], v[72:75]
	v_mfma_f32_16x16x32_bf16 v[68:71], v[184:187], v[224:227], v[68:71]
	v_mfma_f32_16x16x32_bf16 v[64:67], v[192:195], v[224:227], v[64:67]
	s_barrier
; #define PG8_STAGE(bufoff, gbase, voff) do { _Pragma("unroll") for (int _i = 0; _i < 2; ++_i) \
;         __builtin_amdgcn_global_load_lds((const unsigned*)((const char*)(gbase) + (voff)[_i]), (PG8_LAS unsigned*)(lds + (bufoff) + ldsw + _i * 8192), 16, 0, 0); } while (0)
; #define PG8_LDA(dst, b, h) do { _Pragma("unroll") for (int m = 0; m < 4; ++m) _Pragma("unroll") for (int k = 0; k < 2; ++k) dst[m][k] = *(const PG8_LAS bf16x8*)(lds + PG8_SA(b, h) + aoff + m * 2048 + k * 1024); } while (0)
; #define PG8_MMA(ai, bj, At, Bt) do { __builtin_amdgcn_s_setprio(1); _Pragma("unroll") for (int m = 0; m < 4; ++m) _Pragma("unroll") for (int n = 0; n < 2; ++n) _Pragma("unroll") for (int k = 0; k < 2; ++k) \
;         acc[ai][bj][m][n] = __builtin_amdgcn_mfma_f32_16x16x32_bf16(Bt[n][k], At[m][k], acc[ai][bj][m][n], 0, 0, 0); __builtin_amdgcn_s_setprio(0); } while (0)
; #define PG8_WAIT_V(n) asm volatile("s_waitcnt vmcnt(" #n ")" ::: "memory")
; #define PG8_WAIT_L(n) asm volatile("s_waitcnt lgkmcnt(" #n ")" ::: "memory")
; #define PG8_BAR __builtin_amdgcn_s_barrier()
; #define PG8_SCHED __builtin_amdgcn_sched_barrier(0)
; template <class Epi, class Sched, bool ALIGN_EPI = false, bool SP2 = false>
; __device__ __forceinline__ void gemm_phase(PG8_LAS unsigned char* lds, const Gemm g, const Sched& S, const Epi& E) {
;     ...
;             PG8_LDA(At, 1, 1); PG8_STAGE(PG8_SB(1, 0), b3, voffB); PG8_STAGE(PG8_SB(1, 1), b3 + hstep, voffB); PG8_STAGE(PG8_SA(1, 0), a3, voffA);
;             PG8_WAIT_V(8); PG8_WAIT_L(0); PG8_BAR; PG8_MMA(1, 0, At, B0); PG8_MMA(1, 1, At, B1); PG8_BAR; PG8_SCHED;
	s_setprio 0
	s_add_i32 s34, s57, s37
	v_lshl_add_u64 v[152:153], v[152:153], 0, s[14:15]
	s_mov_b32 m0, s34
	ds_read_b128 v[196:199], v163 offset:49152
	ds_read_b128 v[200:203], v163 offset:50176
	ds_read_b128 v[204:207], v163 offset:51200
	ds_read_b128 v[208:211], v163 offset:52224
	ds_read_b128 v[212:215], v163 offset:53248
	ds_read_b128 v[216:219], v163 offset:54272
	ds_read_b128 v[220:223], v163 offset:55296
	ds_read_b128 v[224:227], v163 offset:56320
	global_load_lds_dwordx4 v[152:153], off
	s_add_i32 m0, s34, 0x2000
	s_add_u32 s30, s30, 0x80080
	v_lshl_add_u64 v[152:153], v[228:229], 0, s[14:15]
	s_addc_u32 s31, s31, 0
	s_add_i32 s34, s58, s37
	global_load_lds_dwordx4 v[152:153], off
	v_lshl_add_u64 v[152:153], s[30:31], 0, v[130:131]
	s_mov_b32 m0, s34
	s_nop 0
	global_load_lds_dwordx4 v[152:153], off
	v_lshl_add_u64 v[152:153], s[30:31], 0, v[134:135]
	s_add_i32 m0, s34, 0x2000
	s_nop 0
	global_load_lds_dwordx4 v[152:153], off
	v_lshl_add_u64 v[152:153], v[230:231], 0, s[14:15]
	s_mov_b32 m0, s43
	s_nop 0
	global_load_lds_dwordx4 v[152:153], off
	v_lshl_add_u64 v[152:153], v[232:233], 0, s[14:15]
	s_mov_b32 m0, s44
	s_nop 0
	global_load_lds_dwordx4 v[152:153], off
	s_waitcnt vmcnt(8)
	s_waitcnt lgkmcnt(0)
	s_setprio 1
	s_barrier
	v_mfma_f32_16x16x32_bf16 v[60:63], v[148:151], v[196:199], v[60:63]
	v_mfma_f32_16x16x32_bf16 v[56:59], v[170:173], v[196:199], v[56:59]
	v_mfma_f32_16x16x32_bf16 v[52:55], v[148:151], v[204:207], v[52:55]
	v_mfma_f32_16x16x32_bf16 v[48:51], v[170:173], v[204:207], v[48:51]
	v_mfma_f32_16x16x32_bf16 v[44:47], v[148:151], v[212:215], v[44:47]
	v_mfma_f32_16x16x32_bf16 v[40:43], v[170:173], v[212:215], v[40:43]
	v_mfma_f32_16x16x32_bf16 v[36:39], v[148:151], v[220:223], v[36:39]
	v_mfma_f32_16x16x32_bf16 v[32:35], v[170:173], v[220:223], v[32:35]
	v_mfma_f32_16x16x32_bf16 v[60:63], v[166:169], v[200:203], v[60:63]
	v_mfma_f32_16x16x32_bf16 v[56:59], v[174:177], v[200:203], v[56:59]
	v_mfma_f32_16x16x32_bf16 v[52:55], v[166:169], v[208:211], v[52:55]
	v_mfma_f32_16x16x32_bf16 v[48:51], v[174:177], v[208:211], v[48:51]
	v_mfma_f32_16x16x32_bf16 v[44:47], v[166:169], v[216:219], v[44:47]
	v_mfma_f32_16x16x32_bf16 v[40:43], v[174:177], v[216:219], v[40:43]
	v_mfma_f32_16x16x32_bf16 v[36:39], v[166:169], v[224:227], v[36:39]
	v_mfma_f32_16x16x32_bf16 v[32:35], v[174:177], v[224:227], v[32:35]
	s_setprio 0
	s_setprio 1
	v_mfma_f32_16x16x32_bf16 v[28:31], v[178:181], v[196:199], v[28:31]
	v_mfma_f32_16x16x32_bf16 v[24:27], v[188:191], v[196:199], v[24:27]
	v_mfma_f32_16x16x32_bf16 v[20:23], v[178:181], v[204:207], v[20:23]
	v_mfma_f32_16x16x32_bf16 v[16:19], v[188:191], v[204:207], v[16:19]
	v_mfma_f32_16x16x32_bf16 v[12:15], v[178:181], v[212:215], v[12:15]
	v_mfma_f32_16x16x32_bf16 v[8:11], v[188:191], v[212:215], v[8:11]
	v_mfma_f32_16x16x32_bf16 v[4:7], v[178:181], v[220:223], v[4:7]
	v_mfma_f32_16x16x32_bf16 v[0:3], v[188:191], v[220:223], v[0:3]
	v_mfma_f32_16x16x32_bf16 v[28:31], v[184:187], v[200:203], v[28:31]
	v_mfma_f32_16x16x32_bf16 v[24:27], v[192:195], v[200:203], v[24:27]
	v_mfma_f32_16x16x32_bf16 v[20:23], v[184:187], v[208:211], v[20:23]
	v_mfma_f32_16x16x32_bf16 v[16:19], v[192:195], v[208:211], v[16:19]
	v_mfma_f32_16x16x32_bf16 v[12:15], v[184:187], v[216:219], v[12:15]
	v_mfma_f32_16x16x32_bf16 v[8:11], v[192:195], v[216:219], v[8:11]
	v_mfma_f32_16x16x32_bf16 v[4:7], v[184:187], v[224:227], v[4:7]
	v_mfma_f32_16x16x32_bf16 v[0:3], v[192:195], v[224:227], v[0:3]
	s_barrier
	s_setprio 0
	s_add_i32 s56, s56, 2
	s_add_u32 s28, s28, 0x100
	s_addc_u32 s29, s29, 0
	s_add_u32 s54, s54, 0x100
	s_addc_u32 s55, s55, 0
	s_cmp_gt_u32 s56, 29
	s_cbranch_scc0 .LBB0_253
	s_and_b64 vcc, exec, s[16:17]
	s_cbranch_vccz .LBB0_256
	s_barrier

; #define PG8_STAGE(bufoff, gbase, voff) do { _Pragma("unroll") for (int _i = 0; _i < 2; ++_i) \
;         __builtin_amdgcn_global_load_lds((const unsigned*)((const char*)(gbase) + (voff)[_i]), (PG8_LAS unsigned*)(lds + (bufoff) + ldsw + _i * 8192), 16, 0, 0); } while (0)
; #define PG8_LDA(dst, b, h) do { _Pragma("unroll") for (int m = 0; m < 4; ++m) _Pragma("unroll") for (int k = 0; k < 2; ++k) dst[m][k] = *(const PG8_LAS bf16x8*)(lds + PG8_SA(b, h) + aoff + m * 2048 + k * 1024); } while (0)
; #define PG8_LDB(dst, b, h) do { _Pragma("unroll") for (int n = 0; n < 2; ++n) _Pragma("unroll") for (int k = 0; k < 2; ++k) dst[n][k] = *(const PG8_LAS bf16x8*)(lds + PG8_SB(b, h) + boff + n * 2048 + k * 1024); } while (0)
; #define PG8_MMA(ai, bj, At, Bt) do { __builtin_amdgcn_s_setprio(1); _Pragma("unroll") for (int m = 0; m < 4; ++m) _Pragma("unroll") for (int n = 0; n < 2; ++n) _Pragma("unroll") for (int k = 0; k < 2; ++k) \
;         acc[ai][bj][m][n] = __builtin_amdgcn_mfma_f32_16x16x32_bf16(Bt[n][k], At[m][k], acc[ai][bj][m][n], 0, 0, 0); __builtin_amdgcn_s_setprio(0); } while (0)
; #define PG8_WAIT_V(n) asm volatile("s_waitcnt vmcnt(" #n ")" ::: "memory")
; #define PG8_WAIT_L(n) asm volatile("s_waitcnt lgkmcnt(" #n ")" ::: "memory")
; #define PG8_BAR __builtin_amdgcn_s_barrier()
; #define PG8_SCHED __builtin_amdgcn_sched_barrier(0)
; template <class Epi, class Sched, bool ALIGN_EPI = false, bool SP2 = false>
; __device__ __forceinline__ void gemm_phase(PG8_LAS unsigned char* lds, const Gemm g, const Sched& S, const Epi& E) {
;     ...
;             const char* a2 = last ? nA : cA + (size_t)(t + 2) * kstep; const char* b2 = last ? nB : cB + (size_t)(t + 2) * kstep;
;             const char* a3 = a2 + kstep; const char* b3 = b2 + kstep;
;             if (last && has_next) S.a_ready(nxt);
;             if constexpr (SP2) {
;             PG8_LDB(B0, 0, 0); PG8_LDB(B1, 0, 1); PG8_SCHED; PG8_LDA(At, 0, 0); PG8_STAGE(PG8_SA(1, 1), a1 + hstep, voffA);
;             PG8_WAIT_V(8); PG8_WAIT_L(0); PG8_BAR; PG8_MMA(0, 0, At, B0); PG8_MMA(0, 1, At, B1); PG8_BAR; PG8_SCHED;
;             PG8_LDA(At, 0, 1); PG8_STAGE(PG8_SB(0, 0), b2, voffB); PG8_STAGE(PG8_SB(0, 1), b2 + hstep, voffB); PG8_STAGE(PG8_SA(0, 0), a2, voffA);
;             PG8_WAIT_V(8); PG8_WAIT_L(0); PG8_BAR; PG8_MMA(1, 0, At, B0); PG8_MMA(1, 1, At, B1); PG8_BAR; PG8_SCHED;
.LBB0_953:
	v_add_u32_e32 v134, s50, v165
	ds_read_b128 v[144:147], v134
	ds_read_b128 v[148:151], v134 offset:1024
	ds_read_b128 v[170:173], v134 offset:2048
	ds_read_b128 v[174:177], v134 offset:3072
	v_add_u32_e32 v134, s51, v165
	ds_read_b128 v[178:181], v134
	ds_read_b128 v[184:187], v134 offset:1024
	ds_read_b128 v[188:191], v134 offset:2048
	ds_read_b128 v[192:195], v134 offset:3072
	s_add_u32 s34, s30, 0xfff80080
	s_addc_u32 s35, s31, -1
	s_cmp_eq_u32 s57, 28
	s_cselect_b32 s37, s21, s35
	s_cselect_b32 s36, s27, s34
	s_cselect_b32 s35, s19, s56
	s_cselect_b32 s34, s54, s55
	v_lshl_add_u64 v[152:153], s[30:31], 0, v[136:137]
	s_add_i32 m0, s29, 0xc000
	ds_read_b128 v[196:199], v167
	ds_read_b128 v[200:203], v167 offset:1024
	ds_read_b128 v[204:207], v167 offset:2048
	ds_read_b128 v[208:211], v167 offset:3072
	ds_read_b128 v[212:215], v167 offset:4096
	ds_read_b128 v[216:219], v167 offset:5120
	ds_read_b128 v[220:223], v167 offset:6144
	ds_read_b128 v[224:227], v167 offset:7168
	global_load_lds_dwordx4 v[152:153], off
	v_lshl_add_u64 v[152:153], s[30:31], 0, v[138:139]
	s_add_i32 m0, s29, 0xe000
	s_nop 0
	global_load_lds_dwordx4 v[152:153], off
	s_waitcnt vmcnt(8)
	s_waitcnt lgkmcnt(0)
	s_setprio 1
	s_barrier
	v_mfma_f32_16x16x32_bf16 v[124:127], v[144:147], v[196:199], v[124:127]
	v_mfma_f32_16x16x32_bf16 v[120:123], v[170:173], v[196:199], v[120:123]
	v_mfma_f32_16x16x32_bf16 v[116:119], v[144:147], v[204:207], v[116:119]
	v_mfma_f32_16x16x32_bf16 v[112:115], v[170:173], v[204:207], v[112:115]
	v_mfma_f32_16x16x32_bf16 v[108:111], v[144:147], v[212:215], v[108:111]
	v_mfma_f32_16x16x32_bf16 v[104:107], v[170:173], v[212:215], v[104:107]
	v_mfma_f32_16x16x32_bf16 v[100:103], v[144:147], v[220:223], v[100:103]
	v_mfma_f32_16x16x32_bf16 v[96:99], v[170:173], v[220:223], v[96:99]
	v_mfma_f32_16x16x32_bf16 v[124:127], v[148:151], v[200:203], v[124:127]
	v_mfma_f32_16x16x32_bf16 v[120:123], v[174:177], v[200:203], v[120:123]
	v_mfma_f32_16x16x32_bf16 v[116:119], v[148:151], v[208:211], v[116:119]
	v_mfma_f32_16x16x32_bf16 v[112:115], v[174:177], v[208:211], v[112:115]
	v_mfma_f32_16x16x32_bf16 v[108:111], v[148:151], v[216:219], v[108:111]
	v_mfma_f32_16x16x32_bf16 v[104:107], v[174:177], v[216:219], v[104:107]
	v_mfma_f32_16x16x32_bf16 v[100:103], v[148:151], v[224:227], v[100:103]
	v_mfma_f32_16x16x32_bf16 v[96:99], v[174:177], v[224:227], v[96:99]
	s_setprio 0
	s_setprio 1
	v_mfma_f32_16x16x32_bf16 v[92:95], v[178:181], v[196:199], v[92:95]
	v_mfma_f32_16x16x32_bf16 v[88:91], v[188:191], v[196:199], v[88:91]
	v_mfma_f32_16x16x32_bf16 v[84:87], v[178:181], v[204:207], v[84:87]
	v_mfma_f32_16x16x32_bf16 v[80:83], v[188:191], v[204:207], v[80:83]
	v_mfma_f32_16x16x32_bf16 v[76:79], v[178:181], v[212:215], v[76:79]
	v_mfma_f32_16x16x32_bf16 v[72:75], v[188:191], v[212:215], v[72:75]
	v_mfma_f32_16x16x32_bf16 v[68:71], v[178:181], v[220:223], v[68:71]
	v_mfma_f32_16x16x32_bf16 v[64:67], v[188:191], v[220:223], v[64:67]
	v_mfma_f32_16x16x32_bf16 v[92:95], v[184:187], v[200:203], v[92:95]
	v_mfma_f32_16x16x32_bf16 v[88:91], v[192:195], v[200:203], v[88:91]
	v_mfma_f32_16x16x32_bf16 v[84:87], v[184:187], v[208:211], v[84:87]
	v_mfma_f32_16x16x32_bf16 v[80:83], v[192:195], v[208:211], v[80:83]
	v_mfma_f32_16x16x32_bf16 v[76:79], v[184:187], v[216:219], v[76:79]
	v_mfma_f32_16x16x32_bf16 v[72:75], v[192:195], v[216:219], v[72:75]
	v_mfma_f32_16x16x32_bf16 v[68:71], v[184:187], v[224:227], v[68:71]
	v_mfma_f32_16x16x32_bf16 v[64:67], v[192:195], v[224:227], v[64:67]
	s_barrier
	s_setprio 0
	s_add_i32 s58, s50, s41
	v_lshl_add_u64 v[152:153], s[34:35], 0, v[128:129]
	s_mov_b32 m0, s58
	ds_read_b128 v[196:199], v167 offset:16384
	ds_read_b128 v[200:203], v167 offset:17408
	ds_read_b128 v[204:207], v167 offset:18432
	ds_read_b128 v[208:211], v167 offset:19456
	ds_read_b128 v[212:215], v167 offset:20480
	ds_read_b128 v[216:219], v167 offset:21504
	ds_read_b128 v[220:223], v167 offset:22528
	ds_read_b128 v[224:227], v167 offset:23552
	global_load_lds_dwordx4 v[152:153], off
	s_add_i32 m0, s58, 0x2000
	s_add_u32 s58, s34, 0x80000
	v_lshl_add_u64 v[228:229], s[34:35], 0, v[130:131]
	s_addc_u32 s59, s35, 0
	s_add_i32 s60, s51, s41
	global_load_lds_dwordx4 v[228:229], off
	v_lshl_add_u64 v[230:231], s[58:59], 0, v[128:129]
	s_mov_b32 m0, s60
	v_lshl_add_u64 v[232:233], s[36:37], 0, v[130:131]
	global_load_lds_dwordx4 v[230:231], off
	v_lshl_add_u64 v[230:231], s[58:59], 0, v[130:131]
	s_add_i32 m0, s60, 0x2000
	s_nop 0
	global_load_lds_dwordx4 v[230:231], off
	v_lshl_add_u64 v[230:231], s[36:37], 0, v[128:129]
	s_mov_b32 m0, s29
	s_nop 0
	global_load_lds_dwordx4 v[230:231], off
	s_mov_b32 m0, s42
	s_nop 0
	global_load_lds_dwordx4 v[232:233], off
	s_waitcnt vmcnt(8)
	s_waitcnt lgkmcnt(0)
	s_setprio 1
	s_barrier
; #define PG8_STAGE(bufoff, gbase, voff) do { _Pragma("unroll") for (int _i = 0; _i < 2; ++_i) \
;         __builtin_amdgcn_global_load_lds((const unsigned*)((const char*)(gbase) + (voff)[_i]), (PG8_LAS unsigned*)(lds + (bufoff) + ldsw + _i * 8192), 16, 0, 0); } while (0)
; #define PG8_LDA(dst, b, h) do { _Pragma("unroll") for (int m = 0; m < 4; ++m) _Pragma("unroll") for (int k = 0; k < 2; ++k) dst[m][k] = *(const PG8_LAS bf16x8*)(lds + PG8_SA(b, h) + aoff + m * 2048 + k * 1024); } while (0)
; #define PG8_LDB(dst, b, h) do { _Pragma("unroll") for (int n = 0; n < 2; ++n) _Pragma("unroll") for (int k = 0; k < 2; ++k) dst[n][k] = *(const PG8_LAS bf16x8*)(lds + PG8_SB(b, h) + boff + n * 2048 + k * 1024); } while (0)
; #define PG8_MMA(ai, bj, At, Bt) do { __builtin_amdgcn_s_setprio(1); _Pragma("unroll") for (int m = 0; m < 4; ++m) _Pragma("unroll") for (int n = 0; n < 2; ++n) _Pragma("unroll") for (int k = 0; k < 2; ++k) \
;         acc[ai][bj][m][n] = __builtin_amdgcn_mfma_f32_16x16x32_bf16(Bt[n][k], At[m][k], acc[ai][bj][m][n], 0, 0, 0); __builtin_amdgcn_s_setprio(0); } while (0)
; #define PG8_WAIT_V(n) asm volatile("s_waitcnt vmcnt(" #n ")" ::: "memory")
; #define PG8_WAIT_L(n) asm volatile("s_waitcnt lgkmcnt(" #n ")" ::: "memory")
; #define PG8_BAR __builtin_amdgcn_s_barrier()
; #define PG8_SCHED __builtin_amdgcn_sched_barrier(0)
; template <class Epi, class Sched, bool ALIGN_EPI = false, bool SP2 = false>
; __device__ __forceinline__ void gemm_phase(PG8_LAS unsigned char* lds, const Gemm g, const Sched& S, const Epi& E) {
;     ...
;             PG8_WAIT_V(8); PG8_WAIT_L(0); PG8_BAR; PG8_MMA(1, 0, At, B0); PG8_MMA(1, 1, At, B1); PG8_BAR; PG8_SCHED;
;             PG8_LDB(B0, 1, 0); PG8_LDB(B1, 1, 1); PG8_SCHED; PG8_LDA(At, 1, 0); PG8_STAGE(PG8_SA(0, 1), a2 + hstep, voffA);
;             PG8_WAIT_V(8); PG8_WAIT_L(0); PG8_BAR; PG8_MMA(0, 0, At, B0); PG8_MMA(0, 1, At, B1); PG8_BAR; PG8_SCHED;
	v_mfma_f32_16x16x32_bf16 v[60:63], v[144:147], v[196:199], v[60:63]
	v_mfma_f32_16x16x32_bf16 v[56:59], v[170:173], v[196:199], v[56:59]
	v_mfma_f32_16x16x32_bf16 v[52:55], v[144:147], v[204:207], v[52:55]
	v_mfma_f32_16x16x32_bf16 v[48:51], v[170:173], v[204:207], v[48:51]
	v_mfma_f32_16x16x32_bf16 v[44:47], v[144:147], v[212:215], v[44:47]
	v_mfma_f32_16x16x32_bf16 v[40:43], v[170:173], v[212:215], v[40:43]
	v_mfma_f32_16x16x32_bf16 v[36:39], v[144:147], v[220:223], v[36:39]
	v_mfma_f32_16x16x32_bf16 v[32:35], v[170:173], v[220:223], v[32:35]
	v_mfma_f32_16x16x32_bf16 v[60:63], v[148:151], v[200:203], v[60:63]
	v_mfma_f32_16x16x32_bf16 v[56:59], v[174:177], v[200:203], v[56:59]
	v_mfma_f32_16x16x32_bf16 v[52:55], v[148:151], v[208:211], v[52:55]
	v_mfma_f32_16x16x32_bf16 v[48:51], v[174:177], v[208:211], v[48:51]
	v_mfma_f32_16x16x32_bf16 v[44:47], v[148:151], v[216:219], v[44:47]
	v_mfma_f32_16x16x32_bf16 v[40:43], v[174:177], v[216:219], v[40:43]
	v_mfma_f32_16x16x32_bf16 v[36:39], v[148:151], v[224:227], v[36:39]
	v_mfma_f32_16x16x32_bf16 v[32:35], v[174:177], v[224:227], v[32:35]
	s_setprio 0
	s_setprio 1
	v_mfma_f32_16x16x32_bf16 v[28:31], v[178:181], v[196:199], v[28:31]
	v_mfma_f32_16x16x32_bf16 v[24:27], v[188:191], v[196:199], v[24:27]
	v_mfma_f32_16x16x32_bf16 v[20:23], v[178:181], v[204:207], v[20:23]
	v_mfma_f32_16x16x32_bf16 v[16:19], v[188:191], v[204:207], v[16:19]
	v_mfma_f32_16x16x32_bf16 v[12:15], v[178:181], v[212:215], v[12:15]
	v_mfma_f32_16x16x32_bf16 v[8:11], v[188:191], v[212:215], v[8:11]
	v_mfma_f32_16x16x32_bf16 v[4:7], v[178:181], v[220:223], v[4:7]
	v_mfma_f32_16x16x32_bf16 v[0:3], v[188:191], v[220:223], v[0:3]
	v_mfma_f32_16x16x32_bf16 v[28:31], v[184:187], v[200:203], v[28:31]
	v_mfma_f32_16x16x32_bf16 v[24:27], v[192:195], v[200:203], v[24:27]
	v_mfma_f32_16x16x32_bf16 v[20:23], v[184:187], v[208:211], v[20:23]
	v_mfma_f32_16x16x32_bf16 v[16:19], v[192:195], v[208:211], v[16:19]
	v_mfma_f32_16x16x32_bf16 v[12:15], v[184:187], v[216:219], v[12:15]
	v_mfma_f32_16x16x32_bf16 v[8:11], v[192:195], v[216:219], v[8:11]
	v_mfma_f32_16x16x32_bf16 v[4:7], v[184:187], v[224:227], v[4:7]
	v_mfma_f32_16x16x32_bf16 v[0:3], v[192:195], v[224:227], v[0:3]
	s_barrier
	s_setprio 0
	s_add_i32 s58, 0, 0x18000
	v_add_u32_e32 v134, s58, v165
	s_add_i32 s59, 0, 0x1c000
	ds_read_b128 v[144:147], v134
	ds_read_b128 v[148:151], v134 offset:1024
	ds_read_b128 v[170:173], v134 offset:2048
	ds_read_b128 v[174:177], v134 offset:3072
	v_add_u32_e32 v134, s59, v165
	ds_read_b128 v[178:181], v134
	ds_read_b128 v[184:187], v134 offset:1024
	ds_read_b128 v[188:191], v134 offset:2048
	ds_read_b128 v[192:195], v134 offset:3072
	s_add_u32 s36, s36, 0x80000
	s_addc_u32 s37, s37, 0
	s_mov_b32 m0, s43
	v_lshl_add_u64 v[234:235], s[36:37], 0, v[128:129]
	ds_read_b128 v[196:199], v167 offset:32768
	ds_read_b128 v[200:203], v167 offset:33792
	ds_read_b128 v[204:207], v167 offset:34816
	ds_read_b128 v[208:211], v167 offset:35840
	ds_read_b128 v[212:215], v167 offset:36864
	ds_read_b128 v[216:219], v167 offset:37888
	ds_read_b128 v[220:223], v167 offset:38912
	ds_read_b128 v[224:227], v167 offset:39936
	global_load_lds_dwordx4 v[234:235], off
	v_lshl_add_u64 v[234:235], s[36:37], 0, v[130:131]
	s_mov_b32 m0, s44
	s_nop 0
	global_load_lds_dwordx4 v[234:235], off
	s_waitcnt vmcnt(8)
	s_waitcnt lgkmcnt(0)
	s_setprio 1
	s_barrier
	v_mfma_f32_16x16x32_bf16 v[124:127], v[144:147], v[196:199], v[124:127]
	v_mfma_f32_16x16x32_bf16 v[120:123], v[170:173], v[196:199], v[120:123]
	v_mfma_f32_16x16x32_bf16 v[116:119], v[144:147], v[204:207], v[116:119]
	v_mfma_f32_16x16x32_bf16 v[112:115], v[170:173], v[204:207], v[112:115]
	v_mfma_f32_16x16x32_bf16 v[108:111], v[144:147], v[212:215], v[108:111]
	v_mfma_f32_16x16x32_bf16 v[104:107], v[170:173], v[212:215], v[104:107]
	v_mfma_f32_16x16x32_bf16 v[100:103], v[144:147], v[220:223], v[100:103]
	v_mfma_f32_16x16x32_bf16 v[96:99], v[170:173], v[220:223], v[96:99]
	v_mfma_f32_16x16x32_bf16 v[124:127], v[148:151], v[200:203], v[124:127]
	v_mfma_f32_16x16x32_bf16 v[120:123], v[174:177], v[200:203], v[120:123]
	v_mfma_f32_16x16x32_bf16 v[116:119], v[148:151], v[208:211], v[116:119]
	v_mfma_f32_16x16x32_bf16 v[112:115], v[174:177], v[208:211], v[112:115]
	v_mfma_f32_16x16x32_bf16 v[108:111], v[148:151], v[216:219], v[108:111]
	v_mfma_f32_16x16x32_bf16 v[104:107], v[174:177], v[216:219], v[104:107]
	v_mfma_f32_16x16x32_bf16 v[100:103], v[148:151], v[224:227], v[100:103]
	v_mfma_f32_16x16x32_bf16 v[96:99], v[174:177], v[224:227], v[96:99]
	s_setprio 0
	s_setprio 1
	v_mfma_f32_16x16x32_bf16 v[92:95], v[178:181], v[196:199], v[92:95]
	v_mfma_f32_16x16x32_bf16 v[88:91], v[188:191], v[196:199], v[88:91]
	v_mfma_f32_16x16x32_bf16 v[84:87], v[178:181], v[204:207], v[84:87]
	v_mfma_f32_16x16x32_bf16 v[80:83], v[188:191], v[204:207], v[80:83]
	v_mfma_f32_16x16x32_bf16 v[76:79], v[178:181], v[212:215], v[76:79]
	v_mfma_f32_16x16x32_bf16 v[72:75], v[188:191], v[212:215], v[72:75]
	v_mfma_f32_16x16x32_bf16 v[68:71], v[178:181], v[220:223], v[68:71]
	v_mfma_f32_16x16x32_bf16 v[64:67], v[188:191], v[220:223], v[64:67]
	v_mfma_f32_16x16x32_bf16 v[92:95], v[184:187], v[200:203], v[92:95]
	v_mfma_f32_16x16x32_bf16 v[88:91], v[192:195], v[200:203], v[88:91]
	v_mfma_f32_16x16x32_bf16 v[84:87], v[184:187], v[208:211], v[84:87]
	v_mfma_f32_16x16x32_bf16 v[80:83], v[192:195], v[208:211], v[80:83]
	v_mfma_f32_16x16x32_bf16 v[76:79], v[184:187], v[216:219], v[76:79]
	v_mfma_f32_16x16x32_bf16 v[72:75], v[192:195], v[216:219], v[72:75]
	v_mfma_f32_16x16x32_bf16 v[68:71], v[184:187], v[224:227], v[68:71]
	v_mfma_f32_16x16x32_bf16 v[64:67], v[192:195], v[224:227], v[64:67]
	s_barrier
; #define PG8_STAGE(bufoff, gbase, voff) do { _Pragma("unroll") for (int _i = 0; _i < 2; ++_i) \
;         __builtin_amdgcn_global_load_lds((const unsigned*)((const char*)(gbase) + (voff)[_i]), (PG8_LAS unsigned*)(lds + (bufoff) + ldsw + _i * 8192), 16, 0, 0); } while (0)
; #define PG8_LDA(dst, b, h) do { _Pragma("unroll") for (int m = 0; m < 4; ++m) _Pragma("unroll") for (int k = 0; k < 2; ++k) dst[m][k] = *(const PG8_LAS bf16x8*)(lds + PG8_SA(b, h) + aoff + m * 2048 + k * 1024); } while (0)
; #define PG8_MMA(ai, bj, At, Bt) do { __builtin_amdgcn_s_setprio(1); _Pragma("unroll") for (int m = 0; m < 4; ++m) _Pragma("unroll") for (int n = 0; n < 2; ++n) _Pragma("unroll") for (int k = 0; k < 2; ++k) \
;         acc[ai][bj][m][n] = __builtin_amdgcn_mfma_f32_16x16x32_bf16(Bt[n][k], At[m][k], acc[ai][bj][m][n], 0, 0, 0); __builtin_amdgcn_s_setprio(0); } while (0)
; #define PG8_WAIT_V(n) asm volatile("s_waitcnt vmcnt(" #n ")" ::: "memory")
; #define PG8_WAIT_L(n) asm volatile("s_waitcnt lgkmcnt(" #n ")" ::: "memory")
; #define PG8_BAR __builtin_amdgcn_s_barrier()
; #define PG8_SCHED __builtin_amdgcn_sched_barrier(0)
; template <class Epi, class Sched, bool ALIGN_EPI = false, bool SP2 = false>
; __device__ __forceinline__ void gemm_phase(PG8_LAS unsigned char* lds, const Gemm g, const Sched& S, const Epi& E) {
;     ...
;         for (int t = 0; t < nt; t += 2) {
;             const bool last = (t == nt - 2);
;     ...
;             PG8_LDA(At, 1, 1); PG8_STAGE(PG8_SB(1, 0), b3, voffB); PG8_STAGE(PG8_SB(1, 1), b3 + hstep, voffB); PG8_STAGE(PG8_SA(1, 0), a3, voffA);
;             PG8_WAIT_V(8); PG8_WAIT_L(0); PG8_BAR; PG8_MMA(1, 0, At, B0); PG8_MMA(1, 1, At, B1); PG8_BAR; PG8_SCHED;
	s_setprio 0
	s_add_i32 s36, s58, s41
	v_lshl_add_u64 v[152:153], v[152:153], 0, s[14:15]
	s_mov_b32 m0, s36
	ds_read_b128 v[196:199], v167 offset:49152
	ds_read_b128 v[200:203], v167 offset:50176
	ds_read_b128 v[204:207], v167 offset:51200
	ds_read_b128 v[208:211], v167 offset:52224
	ds_read_b128 v[212:215], v167 offset:53248
	ds_read_b128 v[216:219], v167 offset:54272
	ds_read_b128 v[220:223], v167 offset:55296
	ds_read_b128 v[224:227], v167 offset:56320
	global_load_lds_dwordx4 v[152:153], off
	s_add_i32 m0, s36, 0x2000
	s_add_u32 s34, s34, 0x80080
	v_lshl_add_u64 v[152:153], v[228:229], 0, s[14:15]
	s_addc_u32 s35, s35, 0
	s_add_i32 s36, s59, s41
	global_load_lds_dwordx4 v[152:153], off
	v_lshl_add_u64 v[152:153], s[34:35], 0, v[128:129]
	s_mov_b32 m0, s36
	s_nop 0
	global_load_lds_dwordx4 v[152:153], off
	v_lshl_add_u64 v[152:153], s[34:35], 0, v[130:131]
	s_add_i32 m0, s36, 0x2000
	s_nop 0
	global_load_lds_dwordx4 v[152:153], off
	v_lshl_add_u64 v[152:153], v[230:231], 0, s[14:15]
	s_mov_b32 m0, s45
	s_nop 0
	global_load_lds_dwordx4 v[152:153], off
	v_lshl_add_u64 v[152:153], v[232:233], 0, s[14:15]
	s_mov_b32 m0, s46
	s_nop 0
	global_load_lds_dwordx4 v[152:153], off
	s_waitcnt vmcnt(8)
	s_waitcnt lgkmcnt(0)
	s_setprio 1
	s_barrier
	v_mfma_f32_16x16x32_bf16 v[60:63], v[144:147], v[196:199], v[60:63]
	v_mfma_f32_16x16x32_bf16 v[56:59], v[170:173], v[196:199], v[56:59]
	v_mfma_f32_16x16x32_bf16 v[52:55], v[144:147], v[204:207], v[52:55]
	v_mfma_f32_16x16x32_bf16 v[48:51], v[170:173], v[204:207], v[48:51]
	v_mfma_f32_16x16x32_bf16 v[44:47], v[144:147], v[212:215], v[44:47]
	v_mfma_f32_16x16x32_bf16 v[40:43], v[170:173], v[212:215], v[40:43]
	v_mfma_f32_16x16x32_bf16 v[36:39], v[144:147], v[220:223], v[36:39]
	v_mfma_f32_16x16x32_bf16 v[32:35], v[170:173], v[220:223], v[32:35]
	v_mfma_f32_16x16x32_bf16 v[60:63], v[148:151], v[200:203], v[60:63]
	v_mfma_f32_16x16x32_bf16 v[56:59], v[174:177], v[200:203], v[56:59]
	v_mfma_f32_16x16x32_bf16 v[52:55], v[148:151], v[208:211], v[52:55]
	v_mfma_f32_16x16x32_bf16 v[48:51], v[174:177], v[208:211], v[48:51]
	v_mfma_f32_16x16x32_bf16 v[44:47], v[148:151], v[216:219], v[44:47]
	v_mfma_f32_16x16x32_bf16 v[40:43], v[174:177], v[216:219], v[40:43]
	v_mfma_f32_16x16x32_bf16 v[36:39], v[148:151], v[224:227], v[36:39]
	v_mfma_f32_16x16x32_bf16 v[32:35], v[174:177], v[224:227], v[32:35]
	s_setprio 0
	s_setprio 1
	v_mfma_f32_16x16x32_bf16 v[28:31], v[178:181], v[196:199], v[28:31]
	v_mfma_f32_16x16x32_bf16 v[24:27], v[188:191], v[196:199], v[24:27]
	v_mfma_f32_16x16x32_bf16 v[20:23], v[178:181], v[204:207], v[20:23]
	v_mfma_f32_16x16x32_bf16 v[16:19], v[188:191], v[204:207], v[16:19]
	v_mfma_f32_16x16x32_bf16 v[12:15], v[178:181], v[212:215], v[12:15]
	v_mfma_f32_16x16x32_bf16 v[8:11], v[188:191], v[212:215], v[8:11]
	v_mfma_f32_16x16x32_bf16 v[4:7], v[178:181], v[220:223], v[4:7]
	v_mfma_f32_16x16x32_bf16 v[0:3], v[188:191], v[220:223], v[0:3]
	v_mfma_f32_16x16x32_bf16 v[28:31], v[184:187], v[200:203], v[28:31]
	v_mfma_f32_16x16x32_bf16 v[24:27], v[192:195], v[200:203], v[24:27]
	v_mfma_f32_16x16x32_bf16 v[20:23], v[184:187], v[208:211], v[20:23]
	v_mfma_f32_16x16x32_bf16 v[16:19], v[192:195], v[208:211], v[16:19]
	v_mfma_f32_16x16x32_bf16 v[12:15], v[184:187], v[216:219], v[12:15]
	v_mfma_f32_16x16x32_bf16 v[8:11], v[192:195], v[216:219], v[8:11]
	v_mfma_f32_16x16x32_bf16 v[4:7], v[184:187], v[224:227], v[4:7]
	v_mfma_f32_16x16x32_bf16 v[0:3], v[192:195], v[224:227], v[0:3]
	s_barrier
	s_setprio 0
	s_add_i32 s57, s57, 2
	s_add_u32 s30, s30, 0x100
	s_addc_u32 s31, s31, 0
	s_add_u32 s55, s55, 0x100
	s_addc_u32 s56, s56, 0
	s_cmp_gt_u32 s57, 29
	s_cbranch_scc0 .LBB0_953
	s_and_b64 vcc, exec, s[16:17]
	s_cbranch_vccz .LBB0_956
	s_barrier

; #define PG8_STAGE(bufoff, gbase, voff) do { _Pragma("unroll") for (int _i = 0; _i < 2; ++_i) \
;         __builtin_amdgcn_global_load_lds((const unsigned*)((const char*)(gbase) + (voff)[_i]), (PG8_LAS unsigned*)(lds + (bufoff) + ldsw + _i * 8192), 16, 0, 0); } while (0)
; #define PG8_LDA(dst, b, h) do { _Pragma("unroll") for (int m = 0; m < 4; ++m) _Pragma("unroll") for (int k = 0; k < 2; ++k) dst[m][k] = *(const PG8_LAS bf16x8*)(lds + PG8_SA(b, h) + aoff + m * 2048 + k * 1024); } while (0)
; #define PG8_LDB(dst, b, h) do { _Pragma("unroll") for (int n = 0; n < 2; ++n) _Pragma("unroll") for (int k = 0; k < 2; ++k) dst[n][k] = *(const PG8_LAS bf16x8*)(lds + PG8_SB(b, h) + boff + n * 2048 + k * 1024); } while (0)
; #define PG8_MMA(ai, bj, At, Bt) do { __builtin_amdgcn_s_setprio(1); _Pragma("unroll") for (int m = 0; m < 4; ++m) _Pragma("unroll") for (int n = 0; n < 2; ++n) _Pragma("unroll") for (int k = 0; k < 2; ++k) \
;         acc[ai][bj][m][n] = __builtin_amdgcn_mfma_f32_16x16x32_bf16(Bt[n][k], At[m][k], acc[ai][bj][m][n], 0, 0, 0); __builtin_amdgcn_s_setprio(0); } while (0)
; #define PG8_WAIT_V(n) asm volatile("s_waitcnt vmcnt(" #n ")" ::: "memory")
; #define PG8_WAIT_L(n) asm volatile("s_waitcnt lgkmcnt(" #n ")" ::: "memory")
; #define PG8_BAR __builtin_amdgcn_s_barrier()
; #define PG8_SCHED __builtin_amdgcn_sched_barrier(0)
; template <class Epi, class Sched, bool ALIGN_EPI = false, bool SP2 = false>
; __device__ __forceinline__ void gemm_phase(PG8_LAS unsigned char* lds, const Gemm g, const Sched& S, const Epi& E) {
;     ...
;             const bool last = (t == nt - 2);
;             const char* a1 = cA + (size_t)(t + 1) * kstep;
;             const char* a2 = last ? nA : cA + (size_t)(t + 2) * kstep; const char* b2 = last ? nB : cB + (size_t)(t + 2) * kstep;
;             const char* a3 = a2 + kstep; const char* b3 = b2 + kstep;
;             if (last && has_next) S.a_ready(nxt);
;             if constexpr (SP2) {
;             PG8_LDB(B0, 0, 0); PG8_LDB(B1, 0, 1); PG8_SCHED; PG8_LDA(At, 0, 0); PG8_STAGE(PG8_SA(1, 1), a1 + hstep, voffA);
;             PG8_WAIT_V(8); PG8_WAIT_L(0); PG8_BAR; PG8_MMA(0, 0, At, B0); PG8_MMA(0, 1, At, B1); PG8_BAR; PG8_SCHED;
;             PG8_LDA(At, 0, 1); PG8_STAGE(PG8_SB(0, 0), b2, voffB); PG8_STAGE(PG8_SB(0, 1), b2 + hstep, voffB); PG8_STAGE(PG8_SA(0, 0), a2, voffA);
.LBB0_1071:
	ds_read_b128 v[148:151], v162
	ds_read_b128 v[170:173], v162 offset:1024
	ds_read_b128 v[174:177], v162 offset:2048
	ds_read_b128 v[178:181], v162 offset:3072
	ds_read_b128 v[184:187], v163
	ds_read_b128 v[188:191], v163 offset:1024
	ds_read_b128 v[192:195], v163 offset:2048
	ds_read_b128 v[196:199], v163 offset:3072
	s_add_u32 s34, s30, 0xfff80080
	s_addc_u32 s35, s31, -1
	s_cmp_eq_u32 s58, 28
	s_cselect_b32 s37, s21, s35
	s_cselect_b32 s36, s29, s34
	s_cselect_b32 s35, s19, s57
	s_cselect_b32 s34, s55, s56
	v_lshl_add_u64 v[152:153], s[30:31], 0, v[140:141]
	s_add_i32 m0, s27, 0xc000
	ds_read_b128 v[200:203], v164
	ds_read_b128 v[204:207], v164 offset:1024
	ds_read_b128 v[208:211], v164 offset:2048
	ds_read_b128 v[212:215], v164 offset:3072
	ds_read_b128 v[216:219], v164 offset:4096
	ds_read_b128 v[220:223], v164 offset:5120
	ds_read_b128 v[224:227], v164 offset:6144
	ds_read_b128 v[228:231], v164 offset:7168
	global_load_lds_dwordx4 v[152:153], off
	v_lshl_add_u64 v[152:153], s[30:31], 0, v[142:143]
	s_add_i32 m0, s27, 0xe000
	s_nop 0
	global_load_lds_dwordx4 v[152:153], off
	s_waitcnt vmcnt(8)
	s_waitcnt lgkmcnt(0)
	s_setprio 1
	s_barrier
	v_mfma_f32_16x16x32_bf16 v[124:127], v[148:151], v[200:203], v[124:127]
	v_mfma_f32_16x16x32_bf16 v[120:123], v[174:177], v[200:203], v[120:123]
	v_mfma_f32_16x16x32_bf16 v[116:119], v[148:151], v[208:211], v[116:119]
	v_mfma_f32_16x16x32_bf16 v[112:115], v[174:177], v[208:211], v[112:115]
	v_mfma_f32_16x16x32_bf16 v[108:111], v[148:151], v[216:219], v[108:111]
	v_mfma_f32_16x16x32_bf16 v[104:107], v[174:177], v[216:219], v[104:107]
	v_mfma_f32_16x16x32_bf16 v[100:103], v[148:151], v[224:227], v[100:103]
	v_mfma_f32_16x16x32_bf16 v[96:99], v[174:177], v[224:227], v[96:99]
	v_mfma_f32_16x16x32_bf16 v[124:127], v[170:173], v[204:207], v[124:127]
	v_mfma_f32_16x16x32_bf16 v[120:123], v[178:181], v[204:207], v[120:123]
	v_mfma_f32_16x16x32_bf16 v[116:119], v[170:173], v[212:215], v[116:119]
	v_mfma_f32_16x16x32_bf16 v[112:115], v[178:181], v[212:215], v[112:115]
	v_mfma_f32_16x16x32_bf16 v[108:111], v[170:173], v[220:223], v[108:111]
	v_mfma_f32_16x16x32_bf16 v[104:107], v[178:181], v[220:223], v[104:107]
	v_mfma_f32_16x16x32_bf16 v[100:103], v[170:173], v[228:231], v[100:103]
	v_mfma_f32_16x16x32_bf16 v[96:99], v[178:181], v[228:231], v[96:99]
	s_setprio 0
	s_setprio 1
	v_mfma_f32_16x16x32_bf16 v[92:95], v[184:187], v[200:203], v[92:95]
	v_mfma_f32_16x16x32_bf16 v[88:91], v[192:195], v[200:203], v[88:91]
	v_mfma_f32_16x16x32_bf16 v[84:87], v[184:187], v[208:211], v[84:87]
	v_mfma_f32_16x16x32_bf16 v[80:83], v[192:195], v[208:211], v[80:83]
	v_mfma_f32_16x16x32_bf16 v[76:79], v[184:187], v[216:219], v[76:79]
	v_mfma_f32_16x16x32_bf16 v[72:75], v[192:195], v[216:219], v[72:75]
	v_mfma_f32_16x16x32_bf16 v[68:71], v[184:187], v[224:227], v[68:71]
	v_mfma_f32_16x16x32_bf16 v[64:67], v[192:195], v[224:227], v[64:67]
	v_mfma_f32_16x16x32_bf16 v[92:95], v[188:191], v[204:207], v[92:95]
	v_mfma_f32_16x16x32_bf16 v[88:91], v[196:199], v[204:207], v[88:91]
	v_mfma_f32_16x16x32_bf16 v[84:87], v[188:191], v[212:215], v[84:87]
	v_mfma_f32_16x16x32_bf16 v[80:83], v[196:199], v[212:215], v[80:83]
	v_mfma_f32_16x16x32_bf16 v[76:79], v[188:191], v[220:223], v[76:79]
	v_mfma_f32_16x16x32_bf16 v[72:75], v[196:199], v[220:223], v[72:75]
	v_mfma_f32_16x16x32_bf16 v[68:71], v[188:191], v[228:231], v[68:71]
	v_mfma_f32_16x16x32_bf16 v[64:67], v[196:199], v[228:231], v[64:67]
	s_barrier
	s_setprio 0
	s_add_i32 s59, s52, s33
	v_lshl_add_u64 v[152:153], s[34:35], 0, v[130:131]
	s_mov_b32 m0, s59
	ds_read_b128 v[200:203], v164 offset:16384
	ds_read_b128 v[204:207], v164 offset:17408
	ds_read_b128 v[208:211], v164 offset:18432
	ds_read_b128 v[212:215], v164 offset:19456
	ds_read_b128 v[216:219], v164 offset:20480
	ds_read_b128 v[220:223], v164 offset:21504
	ds_read_b128 v[224:227], v164 offset:22528
	ds_read_b128 v[228:231], v164 offset:23552
	global_load_lds_dwordx4 v[152:153], off
	s_add_i32 m0, s59, 0x2000
	s_add_u32 s60, s34, 0x80000
	v_lshl_add_u64 v[232:233], s[34:35], 0, v[134:135]
	s_addc_u32 s61, s35, 0
	s_add_i32 s59, s53, s33
	global_load_lds_dwordx4 v[232:233], off
	v_lshl_add_u64 v[234:235], s[60:61], 0, v[130:131]
	s_mov_b32 m0, s59
	v_lshl_add_u64 v[236:237], s[36:37], 0, v[132:133]
	global_load_lds_dwordx4 v[234:235], off
	v_lshl_add_u64 v[234:235], s[60:61], 0, v[134:135]
	s_add_i32 m0, s59, 0x2000
	s_nop 0
	global_load_lds_dwordx4 v[234:235], off
	v_lshl_add_u64 v[234:235], s[36:37], 0, v[128:129]
	s_mov_b32 m0, s27
	s_nop 0
	global_load_lds_dwordx4 v[234:235], off
	s_mov_b32 m0, s42
	s_nop 0
	global_load_lds_dwordx4 v[236:237], off
	s_waitcnt vmcnt(8)
	s_waitcnt lgkmcnt(0)
	s_setprio 1
	s_barrier
; #define PG8_STAGE(bufoff, gbase, voff) do { _Pragma("unroll") for (int _i = 0; _i < 2; ++_i) \
;         __builtin_amdgcn_global_load_lds((const unsigned*)((const char*)(gbase) + (voff)[_i]), (PG8_LAS unsigned*)(lds + (bufoff) + ldsw + _i * 8192), 16, 0, 0); } while (0)
; #define PG8_LDA(dst, b, h) do { _Pragma("unroll") for (int m = 0; m < 4; ++m) _Pragma("unroll") for (int k = 0; k < 2; ++k) dst[m][k] = *(const PG8_LAS bf16x8*)(lds + PG8_SA(b, h) + aoff + m * 2048 + k * 1024); } while (0)
; #define PG8_LDB(dst, b, h) do { _Pragma("unroll") for (int n = 0; n < 2; ++n) _Pragma("unroll") for (int k = 0; k < 2; ++k) dst[n][k] = *(const PG8_LAS bf16x8*)(lds + PG8_SB(b, h) + boff + n * 2048 + k * 1024); } while (0)
; #define PG8_MMA(ai, bj, At, Bt) do { __builtin_amdgcn_s_setprio(1); _Pragma("unroll") for (int m = 0; m < 4; ++m) _Pragma("unroll") for (int n = 0; n < 2; ++n) _Pragma("unroll") for (int k = 0; k < 2; ++k) \
;         acc[ai][bj][m][n] = __builtin_amdgcn_mfma_f32_16x16x32_bf16(Bt[n][k], At[m][k], acc[ai][bj][m][n], 0, 0, 0); __builtin_amdgcn_s_setprio(0); } while (0)
; #define PG8_WAIT_V(n) asm volatile("s_waitcnt vmcnt(" #n ")" ::: "memory")
; #define PG8_WAIT_L(n) asm volatile("s_waitcnt lgkmcnt(" #n ")" ::: "memory")
; #define PG8_BAR __builtin_amdgcn_s_barrier()
; #define PG8_SCHED __builtin_amdgcn_sched_barrier(0)
; template <class Epi, class Sched, bool ALIGN_EPI = false, bool SP2 = false>
; __device__ __forceinline__ void gemm_phase(PG8_LAS unsigned char* lds, const Gemm g, const Sched& S, const Epi& E) {
;     ...
;             PG8_WAIT_V(8); PG8_WAIT_L(0); PG8_BAR; PG8_MMA(1, 0, At, B0); PG8_MMA(1, 1, At, B1); PG8_BAR; PG8_SCHED;
;             PG8_LDB(B0, 1, 0); PG8_LDB(B1, 1, 1); PG8_SCHED; PG8_LDA(At, 1, 0); PG8_STAGE(PG8_SA(0, 1), a2 + hstep, voffA);
;             PG8_WAIT_V(8); PG8_WAIT_L(0); PG8_BAR; PG8_MMA(0, 0, At, B0); PG8_MMA(0, 1, At, B1); PG8_BAR; PG8_SCHED;
	v_mfma_f32_16x16x32_bf16 v[60:63], v[148:151], v[200:203], v[60:63]
	v_mfma_f32_16x16x32_bf16 v[56:59], v[174:177], v[200:203], v[56:59]
	v_mfma_f32_16x16x32_bf16 v[52:55], v[148:151], v[208:211], v[52:55]
	v_mfma_f32_16x16x32_bf16 v[48:51], v[174:177], v[208:211], v[48:51]
	v_mfma_f32_16x16x32_bf16 v[44:47], v[148:151], v[216:219], v[44:47]
	v_mfma_f32_16x16x32_bf16 v[40:43], v[174:177], v[216:219], v[40:43]
	v_mfma_f32_16x16x32_bf16 v[36:39], v[148:151], v[224:227], v[36:39]
	v_mfma_f32_16x16x32_bf16 v[32:35], v[174:177], v[224:227], v[32:35]
	v_mfma_f32_16x16x32_bf16 v[60:63], v[170:173], v[204:207], v[60:63]
	v_mfma_f32_16x16x32_bf16 v[56:59], v[178:181], v[204:207], v[56:59]
	v_mfma_f32_16x16x32_bf16 v[52:55], v[170:173], v[212:215], v[52:55]
	v_mfma_f32_16x16x32_bf16 v[48:51], v[178:181], v[212:215], v[48:51]
	v_mfma_f32_16x16x32_bf16 v[44:47], v[170:173], v[220:223], v[44:47]
	v_mfma_f32_16x16x32_bf16 v[40:43], v[178:181], v[220:223], v[40:43]
	v_mfma_f32_16x16x32_bf16 v[36:39], v[170:173], v[228:231], v[36:39]
	v_mfma_f32_16x16x32_bf16 v[32:35], v[178:181], v[228:231], v[32:35]
	s_setprio 0
	s_setprio 1
	v_mfma_f32_16x16x32_bf16 v[28:31], v[184:187], v[200:203], v[28:31]
	v_mfma_f32_16x16x32_bf16 v[24:27], v[192:195], v[200:203], v[24:27]
	v_mfma_f32_16x16x32_bf16 v[20:23], v[184:187], v[208:211], v[20:23]
	v_mfma_f32_16x16x32_bf16 v[16:19], v[192:195], v[208:211], v[16:19]
	v_mfma_f32_16x16x32_bf16 v[12:15], v[184:187], v[216:219], v[12:15]
	v_mfma_f32_16x16x32_bf16 v[8:11], v[192:195], v[216:219], v[8:11]
	v_mfma_f32_16x16x32_bf16 v[4:7], v[184:187], v[224:227], v[4:7]
	v_mfma_f32_16x16x32_bf16 v[0:3], v[192:195], v[224:227], v[0:3]
	v_mfma_f32_16x16x32_bf16 v[28:31], v[188:191], v[204:207], v[28:31]
	v_mfma_f32_16x16x32_bf16 v[24:27], v[196:199], v[204:207], v[24:27]
	v_mfma_f32_16x16x32_bf16 v[20:23], v[188:191], v[212:215], v[20:23]
	v_mfma_f32_16x16x32_bf16 v[16:19], v[196:199], v[212:215], v[16:19]
	v_mfma_f32_16x16x32_bf16 v[12:15], v[188:191], v[220:223], v[12:15]
	v_mfma_f32_16x16x32_bf16 v[8:11], v[196:199], v[220:223], v[8:11]
	v_mfma_f32_16x16x32_bf16 v[4:7], v[188:191], v[228:231], v[4:7]
	v_mfma_f32_16x16x32_bf16 v[0:3], v[196:199], v[228:231], v[0:3]
	s_barrier
	s_setprio 0
	s_add_i32 s59, 0, 0x18000
	v_add_u32_e32 v136, s59, v160
	s_add_i32 s60, 0, 0x1c000
	ds_read_b128 v[148:151], v136
	ds_read_b128 v[170:173], v136 offset:1024
	ds_read_b128 v[174:177], v136 offset:2048
	ds_read_b128 v[178:181], v136 offset:3072
	v_add_u32_e32 v136, s60, v160
	ds_read_b128 v[184:187], v136
	ds_read_b128 v[188:191], v136 offset:1024
	ds_read_b128 v[192:195], v136 offset:2048
	ds_read_b128 v[196:199], v136 offset:3072
	s_add_u32 s36, s36, 0x80000
	s_addc_u32 s37, s37, 0
	s_mov_b32 m0, s43
	v_lshl_add_u64 v[238:239], s[36:37], 0, v[128:129]
	ds_read_b128 v[200:203], v164 offset:32768
	ds_read_b128 v[204:207], v164 offset:33792
	ds_read_b128 v[208:211], v164 offset:34816
	ds_read_b128 v[212:215], v164 offset:35840
	ds_read_b128 v[216:219], v164 offset:36864
	ds_read_b128 v[220:223], v164 offset:37888
	ds_read_b128 v[224:227], v164 offset:38912
	ds_read_b128 v[228:231], v164 offset:39936
	global_load_lds_dwordx4 v[238:239], off
	v_lshl_add_u64 v[238:239], s[36:37], 0, v[132:133]
	s_mov_b32 m0, s44
	s_nop 0
	global_load_lds_dwordx4 v[238:239], off
	s_waitcnt vmcnt(8)
	s_waitcnt lgkmcnt(0)
	s_setprio 1
	s_barrier
	v_mfma_f32_16x16x32_bf16 v[124:127], v[148:151], v[200:203], v[124:127]
	v_mfma_f32_16x16x32_bf16 v[120:123], v[174:177], v[200:203], v[120:123]
	v_mfma_f32_16x16x32_bf16 v[116:119], v[148:151], v[208:211], v[116:119]
	v_mfma_f32_16x16x32_bf16 v[112:115], v[174:177], v[208:211], v[112:115]
	v_mfma_f32_16x16x32_bf16 v[108:111], v[148:151], v[216:219], v[108:111]
	v_mfma_f32_16x16x32_bf16 v[104:107], v[174:177], v[216:219], v[104:107]
	v_mfma_f32_16x16x32_bf16 v[100:103], v[148:151], v[224:227], v[100:103]
	v_mfma_f32_16x16x32_bf16 v[96:99], v[174:177], v[224:227], v[96:99]
	v_mfma_f32_16x16x32_bf16 v[124:127], v[170:173], v[204:207], v[124:127]
	v_mfma_f32_16x16x32_bf16 v[120:123], v[178:181], v[204:207], v[120:123]
	v_mfma_f32_16x16x32_bf16 v[116:119], v[170:173], v[212:215], v[116:119]
	v_mfma_f32_16x16x32_bf16 v[112:115], v[178:181], v[212:215], v[112:115]
	v_mfma_f32_16x16x32_bf16 v[108:111], v[170:173], v[220:223], v[108:111]
	v_mfma_f32_16x16x32_bf16 v[104:107], v[178:181], v[220:223], v[104:107]
	v_mfma_f32_16x16x32_bf16 v[100:103], v[170:173], v[228:231], v[100:103]
	v_mfma_f32_16x16x32_bf16 v[96:99], v[178:181], v[228:231], v[96:99]
	s_setprio 0
	s_setprio 1
	v_mfma_f32_16x16x32_bf16 v[92:95], v[184:187], v[200:203], v[92:95]
	v_mfma_f32_16x16x32_bf16 v[88:91], v[192:195], v[200:203], v[88:91]
	v_mfma_f32_16x16x32_bf16 v[84:87], v[184:187], v[208:211], v[84:87]
	v_mfma_f32_16x16x32_bf16 v[80:83], v[192:195], v[208:211], v[80:83]
	v_mfma_f32_16x16x32_bf16 v[76:79], v[184:187], v[216:219], v[76:79]
	v_mfma_f32_16x16x32_bf16 v[72:75], v[192:195], v[216:219], v[72:75]
	v_mfma_f32_16x16x32_bf16 v[68:71], v[184:187], v[224:227], v[68:71]
	v_mfma_f32_16x16x32_bf16 v[64:67], v[192:195], v[224:227], v[64:67]
	v_mfma_f32_16x16x32_bf16 v[92:95], v[188:191], v[204:207], v[92:95]
	v_mfma_f32_16x16x32_bf16 v[88:91], v[196:199], v[204:207], v[88:91]
	v_mfma_f32_16x16x32_bf16 v[84:87], v[188:191], v[212:215], v[84:87]
	v_mfma_f32_16x16x32_bf16 v[80:83], v[196:199], v[212:215], v[80:83]
	v_mfma_f32_16x16x32_bf16 v[76:79], v[188:191], v[220:223], v[76:79]
	v_mfma_f32_16x16x32_bf16 v[72:75], v[196:199], v[220:223], v[72:75]
	v_mfma_f32_16x16x32_bf16 v[68:71], v[188:191], v[228:231], v[68:71]
	v_mfma_f32_16x16x32_bf16 v[64:67], v[196:199], v[228:231], v[64:67]
	s_barrier
; #define PG8_STAGE(bufoff, gbase, voff) do { _Pragma("unroll") for (int _i = 0; _i < 2; ++_i) \
;         __builtin_amdgcn_global_load_lds((const unsigned*)((const char*)(gbase) + (voff)[_i]), (PG8_LAS unsigned*)(lds + (bufoff) + ldsw + _i * 8192), 16, 0, 0); } while (0)
; #define PG8_LDA(dst, b, h) do { _Pragma("unroll") for (int m = 0; m < 4; ++m) _Pragma("unroll") for (int k = 0; k < 2; ++k) dst[m][k] = *(const PG8_LAS bf16x8*)(lds + PG8_SA(b, h) + aoff + m * 2048 + k * 1024); } while (0)
; #define PG8_MMA(ai, bj, At, Bt) do { __builtin_amdgcn_s_setprio(1); _Pragma("unroll") for (int m = 0; m < 4; ++m) _Pragma("unroll") for (int n = 0; n < 2; ++n) _Pragma("unroll") for (int k = 0; k < 2; ++k) \
;         acc[ai][bj][m][n] = __builtin_amdgcn_mfma_f32_16x16x32_bf16(Bt[n][k], At[m][k], acc[ai][bj][m][n], 0, 0, 0); __builtin_amdgcn_s_setprio(0); } while (0)
; #define PG8_WAIT_V(n) asm volatile("s_waitcnt vmcnt(" #n ")" ::: "memory")
; #define PG8_WAIT_L(n) asm volatile("s_waitcnt lgkmcnt(" #n ")" ::: "memory")
; #define PG8_BAR __builtin_amdgcn_s_barrier()
; #define PG8_SCHED __builtin_amdgcn_sched_barrier(0)
; template <class Epi, class Sched, bool ALIGN_EPI = false, bool SP2 = false>
; __device__ __forceinline__ void gemm_phase(PG8_LAS unsigned char* lds, const Gemm g, const Sched& S, const Epi& E) {
;     ...
;         for (int t = 0; t < nt; t += 2) {
;             const bool last = (t == nt - 2);
;     ...
;             PG8_LDA(At, 1, 1); PG8_STAGE(PG8_SB(1, 0), b3, voffB); PG8_STAGE(PG8_SB(1, 1), b3 + hstep, voffB); PG8_STAGE(PG8_SA(1, 0), a3, voffA);
;             PG8_WAIT_V(8); PG8_WAIT_L(0); PG8_BAR; PG8_MMA(1, 0, At, B0); PG8_MMA(1, 1, At, B1); PG8_BAR; PG8_SCHED;
	s_setprio 0
	s_add_i32 s36, s59, s33
	v_lshl_add_u64 v[152:153], v[152:153], 0, s[14:15]
	s_mov_b32 m0, s36
	ds_read_b128 v[200:203], v164 offset:49152
	ds_read_b128 v[204:207], v164 offset:50176
	ds_read_b128 v[208:211], v164 offset:51200
	ds_read_b128 v[212:215], v164 offset:52224
	ds_read_b128 v[216:219], v164 offset:53248
	ds_read_b128 v[220:223], v164 offset:54272
	ds_read_b128 v[224:227], v164 offset:55296
	ds_read_b128 v[228:231], v164 offset:56320
	global_load_lds_dwordx4 v[152:153], off
	s_add_i32 m0, s36, 0x2000
	s_add_u32 s34, s34, 0x80080
	v_lshl_add_u64 v[152:153], v[232:233], 0, s[14:15]
	s_addc_u32 s35, s35, 0
	s_add_i32 s36, s60, s33
	global_load_lds_dwordx4 v[152:153], off
	v_lshl_add_u64 v[152:153], s[34:35], 0, v[130:131]
	s_mov_b32 m0, s36
	s_nop 0
	global_load_lds_dwordx4 v[152:153], off
	v_lshl_add_u64 v[152:153], s[34:35], 0, v[134:135]
	s_add_i32 m0, s36, 0x2000
	s_nop 0
	global_load_lds_dwordx4 v[152:153], off
	v_lshl_add_u64 v[152:153], v[234:235], 0, s[14:15]
	s_mov_b32 m0, s46
	s_nop 0
	global_load_lds_dwordx4 v[152:153], off
	v_lshl_add_u64 v[152:153], v[236:237], 0, s[14:15]
	s_mov_b32 m0, s47
	s_nop 0
	global_load_lds_dwordx4 v[152:153], off
	s_waitcnt vmcnt(8)
	s_waitcnt lgkmcnt(0)
	s_setprio 1
	s_barrier
	v_mfma_f32_16x16x32_bf16 v[60:63], v[148:151], v[200:203], v[60:63]
	v_mfma_f32_16x16x32_bf16 v[56:59], v[174:177], v[200:203], v[56:59]
	v_mfma_f32_16x16x32_bf16 v[52:55], v[148:151], v[208:211], v[52:55]
	v_mfma_f32_16x16x32_bf16 v[48:51], v[174:177], v[208:211], v[48:51]
	v_mfma_f32_16x16x32_bf16 v[44:47], v[148:151], v[216:219], v[44:47]
	v_mfma_f32_16x16x32_bf16 v[40:43], v[174:177], v[216:219], v[40:43]
	v_mfma_f32_16x16x32_bf16 v[36:39], v[148:151], v[224:227], v[36:39]
	v_mfma_f32_16x16x32_bf16 v[32:35], v[174:177], v[224:227], v[32:35]
	v_mfma_f32_16x16x32_bf16 v[60:63], v[170:173], v[204:207], v[60:63]
	v_mfma_f32_16x16x32_bf16 v[56:59], v[178:181], v[204:207], v[56:59]
	v_mfma_f32_16x16x32_bf16 v[52:55], v[170:173], v[212:215], v[52:55]
	v_mfma_f32_16x16x32_bf16 v[48:51], v[178:181], v[212:215], v[48:51]
	v_mfma_f32_16x16x32_bf16 v[44:47], v[170:173], v[220:223], v[44:47]
	v_mfma_f32_16x16x32_bf16 v[40:43], v[178:181], v[220:223], v[40:43]
	v_mfma_f32_16x16x32_bf16 v[36:39], v[170:173], v[228:231], v[36:39]
	v_mfma_f32_16x16x32_bf16 v[32:35], v[178:181], v[228:231], v[32:35]
	s_setprio 0
	s_setprio 1
	v_mfma_f32_16x16x32_bf16 v[28:31], v[184:187], v[200:203], v[28:31]
	v_mfma_f32_16x16x32_bf16 v[24:27], v[192:195], v[200:203], v[24:27]
	v_mfma_f32_16x16x32_bf16 v[20:23], v[184:187], v[208:211], v[20:23]
	v_mfma_f32_16x16x32_bf16 v[16:19], v[192:195], v[208:211], v[16:19]
	v_mfma_f32_16x16x32_bf16 v[12:15], v[184:187], v[216:219], v[12:15]
	v_mfma_f32_16x16x32_bf16 v[8:11], v[192:195], v[216:219], v[8:11]
	v_mfma_f32_16x16x32_bf16 v[4:7], v[184:187], v[224:227], v[4:7]
	v_mfma_f32_16x16x32_bf16 v[0:3], v[192:195], v[224:227], v[0:3]
	v_mfma_f32_16x16x32_bf16 v[28:31], v[188:191], v[204:207], v[28:31]
	v_mfma_f32_16x16x32_bf16 v[24:27], v[196:199], v[204:207], v[24:27]
	v_mfma_f32_16x16x32_bf16 v[20:23], v[188:191], v[212:215], v[20:23]
	v_mfma_f32_16x16x32_bf16 v[16:19], v[196:199], v[212:215], v[16:19]
	v_mfma_f32_16x16x32_bf16 v[12:15], v[188:191], v[220:223], v[12:15]
	v_mfma_f32_16x16x32_bf16 v[8:11], v[196:199], v[220:223], v[8:11]
	v_mfma_f32_16x16x32_bf16 v[4:7], v[188:191], v[228:231], v[4:7]
	v_mfma_f32_16x16x32_bf16 v[0:3], v[196:199], v[228:231], v[0:3]
	s_barrier
	s_setprio 0
	s_add_i32 s58, s58, 2
	s_add_u32 s30, s30, 0x100
	s_addc_u32 s31, s31, 0
	s_add_u32 s56, s56, 0x100
	s_addc_u32 s57, s57, 0
	s_cmp_gt_u32 s58, 29
	s_cbranch_scc0 .LBB0_1071
	s_and_b64 vcc, exec, s[16:17]
	s_cbranch_vccz .LBB0_1074
	s_barrier

; #define PG8_STAGE(bufoff, gbase, voff) do { _Pragma("unroll") for (int _i = 0; _i < 2; ++_i) \
;         __builtin_amdgcn_global_load_lds((const unsigned*)((const char*)(gbase) + (voff)[_i]), (PG8_LAS unsigned*)(lds + (bufoff) + ldsw + _i * 8192), 16, 0, 0); } while (0)
; #define PG8_LDA(dst, b, h) do { _Pragma("unroll") for (int m = 0; m < 4; ++m) _Pragma("unroll") for (int k = 0; k < 2; ++k) dst[m][k] = *(const PG8_LAS bf16x8*)(lds + PG8_SA(b, h) + aoff + m * 2048 + k * 1024); } while (0)
; #define PG8_LDB(dst, b, h) do { _Pragma("unroll") for (int n = 0; n < 2; ++n) _Pragma("unroll") for (int k = 0; k < 2; ++k) dst[n][k] = *(const PG8_LAS bf16x8*)(lds + PG8_SB(b, h) + boff + n * 2048 + k * 1024); } while (0)
; #define PG8_MMA(ai, bj, At, Bt) do { __builtin_amdgcn_s_setprio(1); _Pragma("unroll") for (int m = 0; m < 4; ++m) _Pragma("unroll") for (int n = 0; n < 2; ++n) _Pragma("unroll") for (int k = 0; k < 2; ++k) \
;         acc[ai][bj][m][n] = __builtin_amdgcn_mfma_f32_16x16x32_bf16(Bt[n][k], At[m][k], acc[ai][bj][m][n], 0, 0, 0); __builtin_amdgcn_s_setprio(0); } while (0)
; #define PG8_WAIT_V(n) asm volatile("s_waitcnt vmcnt(" #n ")" ::: "memory")
; #define PG8_WAIT_L(n) asm volatile("s_waitcnt lgkmcnt(" #n ")" ::: "memory")
; #define PG8_BAR __builtin_amdgcn_s_barrier()
; #define PG8_SCHED __builtin_amdgcn_sched_barrier(0)
; template <class Epi, class Sched, bool ALIGN_EPI = false, bool SP2 = false>
; __device__ __forceinline__ void gemm_phase(PG8_LAS unsigned char* lds, const Gemm g, const Sched& S, const Epi& E) {
;     ...
;             const bool last = (t == nt - 2);
;             const char* a1 = cA + (size_t)(t + 1) * kstep;
;             const char* a2 = last ? nA : cA + (size_t)(t + 2) * kstep; const char* b2 = last ? nB : cB + (size_t)(t + 2) * kstep;
;             const char* a3 = a2 + kstep; const char* b3 = b2 + kstep;
;             if (last && has_next) S.a_ready(nxt);
;             if constexpr (SP2) {
;             PG8_LDB(B0, 0, 0); PG8_LDB(B1, 0, 1); PG8_SCHED; PG8_LDA(At, 0, 0); PG8_STAGE(PG8_SA(1, 1), a1 + hstep, voffA);
;             PG8_WAIT_V(8); PG8_WAIT_L(0); PG8_BAR; PG8_MMA(0, 0, At, B0); PG8_MMA(0, 1, At, B1); PG8_BAR; PG8_SCHED;
;             PG8_LDA(At, 0, 1); PG8_STAGE(PG8_SB(0, 0), b2, voffB); PG8_STAGE(PG8_SB(0, 1), b2 + hstep, voffB); PG8_STAGE(PG8_SA(0, 0), a2, voffA);
.LBB0_1343:
	v_add_u32_e32 v134, s46, v161
	ds_read_b128 v[144:147], v134
	ds_read_b128 v[166:169], v134 offset:1024
	ds_read_b128 v[170:173], v134 offset:2048
	ds_read_b128 v[174:177], v134 offset:3072
	v_add_u32_e32 v134, s47, v161
	ds_read_b128 v[178:181], v134
	ds_read_b128 v[184:187], v134 offset:1024
	ds_read_b128 v[188:191], v134 offset:2048
	ds_read_b128 v[192:195], v134 offset:3072
	s_add_u32 s34, s30, 0xfff00080
	s_addc_u32 s35, s31, -1
	s_cmp_eq_u32 s56, 60
	s_cselect_b32 s37, s21, s35
	s_cselect_b32 s36, s27, s34
	s_cselect_b32 s35, s19, s55
	s_cselect_b32 s34, s49, s54
	v_lshl_add_u64 v[148:149], s[30:31], 0, v[136:137]
	s_add_i32 m0, s29, 0xc000
	ds_read_b128 v[196:199], v163
	ds_read_b128 v[200:203], v163 offset:1024
	ds_read_b128 v[204:207], v163 offset:2048
	ds_read_b128 v[208:211], v163 offset:3072
	ds_read_b128 v[212:215], v163 offset:4096
	ds_read_b128 v[216:219], v163 offset:5120
	ds_read_b128 v[220:223], v163 offset:6144
	ds_read_b128 v[224:227], v163 offset:7168
	global_load_lds_dwordx4 v[148:149], off
	v_lshl_add_u64 v[148:149], s[30:31], 0, v[138:139]
	s_add_i32 m0, s29, 0xe000
	s_nop 0
	global_load_lds_dwordx4 v[148:149], off
	s_waitcnt vmcnt(8)
	s_waitcnt lgkmcnt(0)
	s_setprio 1
	s_barrier
	v_mfma_f32_16x16x32_bf16 v[120:123], v[144:147], v[196:199], v[120:123]
	v_mfma_f32_16x16x32_bf16 v[124:127], v[170:173], v[196:199], v[124:127]
	v_mfma_f32_16x16x32_bf16 v[112:115], v[144:147], v[204:207], v[112:115]
	v_mfma_f32_16x16x32_bf16 v[116:119], v[170:173], v[204:207], v[116:119]
	v_mfma_f32_16x16x32_bf16 v[104:107], v[144:147], v[212:215], v[104:107]
	v_mfma_f32_16x16x32_bf16 v[108:111], v[170:173], v[212:215], v[108:111]
	v_mfma_f32_16x16x32_bf16 v[96:99], v[144:147], v[220:223], v[96:99]
	v_mfma_f32_16x16x32_bf16 v[100:103], v[170:173], v[220:223], v[100:103]
	v_mfma_f32_16x16x32_bf16 v[120:123], v[166:169], v[200:203], v[120:123]
	v_mfma_f32_16x16x32_bf16 v[124:127], v[174:177], v[200:203], v[124:127]
	v_mfma_f32_16x16x32_bf16 v[112:115], v[166:169], v[208:211], v[112:115]
	v_mfma_f32_16x16x32_bf16 v[116:119], v[174:177], v[208:211], v[116:119]
	v_mfma_f32_16x16x32_bf16 v[104:107], v[166:169], v[216:219], v[104:107]
	v_mfma_f32_16x16x32_bf16 v[108:111], v[174:177], v[216:219], v[108:111]
	v_mfma_f32_16x16x32_bf16 v[96:99], v[166:169], v[224:227], v[96:99]
	v_mfma_f32_16x16x32_bf16 v[100:103], v[174:177], v[224:227], v[100:103]
	s_setprio 0
	s_setprio 1
	v_mfma_f32_16x16x32_bf16 v[76:79], v[178:181], v[196:199], v[76:79]
	v_mfma_f32_16x16x32_bf16 v[92:95], v[188:191], v[196:199], v[92:95]
	v_mfma_f32_16x16x32_bf16 v[72:75], v[178:181], v[204:207], v[72:75]
	v_mfma_f32_16x16x32_bf16 v[88:91], v[188:191], v[204:207], v[88:91]
	v_mfma_f32_16x16x32_bf16 v[68:71], v[178:181], v[212:215], v[68:71]
	v_mfma_f32_16x16x32_bf16 v[84:87], v[188:191], v[212:215], v[84:87]
	v_mfma_f32_16x16x32_bf16 v[64:67], v[178:181], v[220:223], v[64:67]
	v_mfma_f32_16x16x32_bf16 v[80:83], v[188:191], v[220:223], v[80:83]
	v_mfma_f32_16x16x32_bf16 v[76:79], v[184:187], v[200:203], v[76:79]
	v_mfma_f32_16x16x32_bf16 v[92:95], v[192:195], v[200:203], v[92:95]
	v_mfma_f32_16x16x32_bf16 v[72:75], v[184:187], v[208:211], v[72:75]
	v_mfma_f32_16x16x32_bf16 v[88:91], v[192:195], v[208:211], v[88:91]
	v_mfma_f32_16x16x32_bf16 v[68:71], v[184:187], v[216:219], v[68:71]
	v_mfma_f32_16x16x32_bf16 v[84:87], v[192:195], v[216:219], v[84:87]
	v_mfma_f32_16x16x32_bf16 v[64:67], v[184:187], v[224:227], v[64:67]
	v_mfma_f32_16x16x32_bf16 v[80:83], v[192:195], v[224:227], v[80:83]
	s_barrier
	s_setprio 0
	s_add_i32 s57, s46, s33
	v_lshl_add_u64 v[148:149], s[34:35], 0, v[128:129]
	s_mov_b32 m0, s57
	ds_read_b128 v[196:199], v163 offset:16384
	ds_read_b128 v[200:203], v163 offset:17408
	ds_read_b128 v[204:207], v163 offset:18432
	ds_read_b128 v[208:211], v163 offset:19456
	ds_read_b128 v[212:215], v163 offset:20480
	ds_read_b128 v[216:219], v163 offset:21504
	ds_read_b128 v[220:223], v163 offset:22528
	ds_read_b128 v[224:227], v163 offset:23552
	global_load_lds_dwordx4 v[148:149], off
	s_add_i32 m0, s57, 0x2000
	s_add_u32 s58, s34, 0x100000
	v_lshl_add_u64 v[228:229], s[34:35], 0, v[130:131]
	s_addc_u32 s59, s35, 0
	s_add_i32 s57, s47, s33
	global_load_lds_dwordx4 v[228:229], off
	v_lshl_add_u64 v[230:231], s[58:59], 0, v[128:129]
	s_mov_b32 m0, s57
	v_lshl_add_u64 v[232:233], s[36:37], 0, v[130:131]
	global_load_lds_dwordx4 v[230:231], off
	v_lshl_add_u64 v[230:231], s[58:59], 0, v[130:131]
	s_add_i32 m0, s57, 0x2000
	s_nop 0
	global_load_lds_dwordx4 v[230:231], off
	v_lshl_add_u64 v[230:231], s[36:37], 0, v[128:129]
	s_mov_b32 m0, s29
	s_nop 0
	global_load_lds_dwordx4 v[230:231], off
	s_mov_b32 m0, s38
	s_nop 0
	global_load_lds_dwordx4 v[232:233], off
	s_waitcnt vmcnt(8)
	s_waitcnt lgkmcnt(0)
	s_setprio 1
	s_barrier
; #define PG8_STAGE(bufoff, gbase, voff) do { _Pragma("unroll") for (int _i = 0; _i < 2; ++_i) \
;         __builtin_amdgcn_global_load_lds((const unsigned*)((const char*)(gbase) + (voff)[_i]), (PG8_LAS unsigned*)(lds + (bufoff) + ldsw + _i * 8192), 16, 0, 0); } while (0)
; #define PG8_LDA(dst, b, h) do { _Pragma("unroll") for (int m = 0; m < 4; ++m) _Pragma("unroll") for (int k = 0; k < 2; ++k) dst[m][k] = *(const PG8_LAS bf16x8*)(lds + PG8_SA(b, h) + aoff + m * 2048 + k * 1024); } while (0)
; #define PG8_LDB(dst, b, h) do { _Pragma("unroll") for (int n = 0; n < 2; ++n) _Pragma("unroll") for (int k = 0; k < 2; ++k) dst[n][k] = *(const PG8_LAS bf16x8*)(lds + PG8_SB(b, h) + boff + n * 2048 + k * 1024); } while (0)
; #define PG8_MMA(ai, bj, At, Bt) do { __builtin_amdgcn_s_setprio(1); _Pragma("unroll") for (int m = 0; m < 4; ++m) _Pragma("unroll") for (int n = 0; n < 2; ++n) _Pragma("unroll") for (int k = 0; k < 2; ++k) \
;         acc[ai][bj][m][n] = __builtin_amdgcn_mfma_f32_16x16x32_bf16(Bt[n][k], At[m][k], acc[ai][bj][m][n], 0, 0, 0); __builtin_amdgcn_s_setprio(0); } while (0)
; #define PG8_WAIT_V(n) asm volatile("s_waitcnt vmcnt(" #n ")" ::: "memory")
; #define PG8_WAIT_L(n) asm volatile("s_waitcnt lgkmcnt(" #n ")" ::: "memory")
; #define PG8_BAR __builtin_amdgcn_s_barrier()
; #define PG8_SCHED __builtin_amdgcn_sched_barrier(0)
; template <class Epi, class Sched, bool ALIGN_EPI = false, bool SP2 = false>
; __device__ __forceinline__ void gemm_phase(PG8_LAS unsigned char* lds, const Gemm g, const Sched& S, const Epi& E) {
;     ...
;             PG8_WAIT_V(8); PG8_WAIT_L(0); PG8_BAR; PG8_MMA(1, 0, At, B0); PG8_MMA(1, 1, At, B1); PG8_BAR; PG8_SCHED;
;             PG8_LDB(B0, 1, 0); PG8_LDB(B1, 1, 1); PG8_SCHED; PG8_LDA(At, 1, 0); PG8_STAGE(PG8_SA(0, 1), a2 + hstep, voffA);
;             PG8_WAIT_V(8); PG8_WAIT_L(0); PG8_BAR; PG8_MMA(0, 0, At, B0); PG8_MMA(0, 1, At, B1); PG8_BAR; PG8_SCHED;
	v_mfma_f32_16x16x32_bf16 v[56:59], v[144:147], v[196:199], v[56:59]
	v_mfma_f32_16x16x32_bf16 v[60:63], v[170:173], v[196:199], v[60:63]
	v_mfma_f32_16x16x32_bf16 v[48:51], v[144:147], v[204:207], v[48:51]
	v_mfma_f32_16x16x32_bf16 v[52:55], v[170:173], v[204:207], v[52:55]
	v_mfma_f32_16x16x32_bf16 v[40:43], v[144:147], v[212:215], v[40:43]
	v_mfma_f32_16x16x32_bf16 v[44:47], v[170:173], v[212:215], v[44:47]
	v_mfma_f32_16x16x32_bf16 v[32:35], v[144:147], v[220:223], v[32:35]
	v_mfma_f32_16x16x32_bf16 v[36:39], v[170:173], v[220:223], v[36:39]
	v_mfma_f32_16x16x32_bf16 v[56:59], v[166:169], v[200:203], v[56:59]
	v_mfma_f32_16x16x32_bf16 v[60:63], v[174:177], v[200:203], v[60:63]
	v_mfma_f32_16x16x32_bf16 v[48:51], v[166:169], v[208:211], v[48:51]
	v_mfma_f32_16x16x32_bf16 v[52:55], v[174:177], v[208:211], v[52:55]
	v_mfma_f32_16x16x32_bf16 v[40:43], v[166:169], v[216:219], v[40:43]
	v_mfma_f32_16x16x32_bf16 v[44:47], v[174:177], v[216:219], v[44:47]
	v_mfma_f32_16x16x32_bf16 v[32:35], v[166:169], v[224:227], v[32:35]
	v_mfma_f32_16x16x32_bf16 v[36:39], v[174:177], v[224:227], v[36:39]
	s_setprio 0
	s_setprio 1
	v_mfma_f32_16x16x32_bf16 v[12:15], v[178:181], v[196:199], v[12:15]
	v_mfma_f32_16x16x32_bf16 v[28:31], v[188:191], v[196:199], v[28:31]
	v_mfma_f32_16x16x32_bf16 v[8:11], v[178:181], v[204:207], v[8:11]
	v_mfma_f32_16x16x32_bf16 v[24:27], v[188:191], v[204:207], v[24:27]
	v_mfma_f32_16x16x32_bf16 v[4:7], v[178:181], v[212:215], v[4:7]
	v_mfma_f32_16x16x32_bf16 v[20:23], v[188:191], v[212:215], v[20:23]
	v_mfma_f32_16x16x32_bf16 v[0:3], v[178:181], v[220:223], v[0:3]
	v_mfma_f32_16x16x32_bf16 v[16:19], v[188:191], v[220:223], v[16:19]
	v_mfma_f32_16x16x32_bf16 v[12:15], v[184:187], v[200:203], v[12:15]
	v_mfma_f32_16x16x32_bf16 v[28:31], v[192:195], v[200:203], v[28:31]
	v_mfma_f32_16x16x32_bf16 v[8:11], v[184:187], v[208:211], v[8:11]
	v_mfma_f32_16x16x32_bf16 v[24:27], v[192:195], v[208:211], v[24:27]
	v_mfma_f32_16x16x32_bf16 v[4:7], v[184:187], v[216:219], v[4:7]
	v_mfma_f32_16x16x32_bf16 v[20:23], v[192:195], v[216:219], v[20:23]
	v_mfma_f32_16x16x32_bf16 v[0:3], v[184:187], v[224:227], v[0:3]
	v_mfma_f32_16x16x32_bf16 v[16:19], v[192:195], v[224:227], v[16:19]
	s_barrier
	s_setprio 0
	s_add_i32 s57, 0, 0x18000
	v_add_u32_e32 v134, s57, v161
	s_add_i32 s58, 0, 0x1c000
	ds_read_b128 v[144:147], v134
	ds_read_b128 v[166:169], v134 offset:1024
	ds_read_b128 v[170:173], v134 offset:2048
	ds_read_b128 v[174:177], v134 offset:3072
	v_add_u32_e32 v134, s58, v161
	ds_read_b128 v[178:181], v134
	ds_read_b128 v[184:187], v134 offset:1024
	ds_read_b128 v[188:191], v134 offset:2048
	ds_read_b128 v[192:195], v134 offset:3072
	s_add_u32 s36, s36, 0x100000
	s_addc_u32 s37, s37, 0
	s_mov_b32 m0, s39
	v_lshl_add_u64 v[234:235], s[36:37], 0, v[128:129]
	ds_read_b128 v[196:199], v163 offset:32768
	ds_read_b128 v[200:203], v163 offset:33792
	ds_read_b128 v[204:207], v163 offset:34816
	ds_read_b128 v[208:211], v163 offset:35840
	ds_read_b128 v[212:215], v163 offset:36864
	ds_read_b128 v[216:219], v163 offset:37888
	ds_read_b128 v[220:223], v163 offset:38912
	ds_read_b128 v[224:227], v163 offset:39936
	global_load_lds_dwordx4 v[234:235], off
	v_lshl_add_u64 v[234:235], s[36:37], 0, v[130:131]
	s_mov_b32 m0, s40
	s_nop 0
	global_load_lds_dwordx4 v[234:235], off
	s_waitcnt vmcnt(8)
	s_waitcnt lgkmcnt(0)
	s_setprio 1
	s_barrier
	v_mfma_f32_16x16x32_bf16 v[120:123], v[144:147], v[196:199], v[120:123]
	v_mfma_f32_16x16x32_bf16 v[124:127], v[170:173], v[196:199], v[124:127]
	v_mfma_f32_16x16x32_bf16 v[112:115], v[144:147], v[204:207], v[112:115]
	v_mfma_f32_16x16x32_bf16 v[116:119], v[170:173], v[204:207], v[116:119]
	v_mfma_f32_16x16x32_bf16 v[104:107], v[144:147], v[212:215], v[104:107]
	v_mfma_f32_16x16x32_bf16 v[108:111], v[170:173], v[212:215], v[108:111]
	v_mfma_f32_16x16x32_bf16 v[96:99], v[144:147], v[220:223], v[96:99]
	v_mfma_f32_16x16x32_bf16 v[100:103], v[170:173], v[220:223], v[100:103]
	v_mfma_f32_16x16x32_bf16 v[120:123], v[166:169], v[200:203], v[120:123]
	v_mfma_f32_16x16x32_bf16 v[124:127], v[174:177], v[200:203], v[124:127]
	v_mfma_f32_16x16x32_bf16 v[112:115], v[166:169], v[208:211], v[112:115]
	v_mfma_f32_16x16x32_bf16 v[116:119], v[174:177], v[208:211], v[116:119]
	v_mfma_f32_16x16x32_bf16 v[104:107], v[166:169], v[216:219], v[104:107]
	v_mfma_f32_16x16x32_bf16 v[108:111], v[174:177], v[216:219], v[108:111]
	v_mfma_f32_16x16x32_bf16 v[96:99], v[166:169], v[224:227], v[96:99]
	v_mfma_f32_16x16x32_bf16 v[100:103], v[174:177], v[224:227], v[100:103]
	s_setprio 0
	s_setprio 1
	v_mfma_f32_16x16x32_bf16 v[76:79], v[178:181], v[196:199], v[76:79]
	v_mfma_f32_16x16x32_bf16 v[92:95], v[188:191], v[196:199], v[92:95]
	v_mfma_f32_16x16x32_bf16 v[72:75], v[178:181], v[204:207], v[72:75]
	v_mfma_f32_16x16x32_bf16 v[88:91], v[188:191], v[204:207], v[88:91]
	v_mfma_f32_16x16x32_bf16 v[68:71], v[178:181], v[212:215], v[68:71]
	v_mfma_f32_16x16x32_bf16 v[84:87], v[188:191], v[212:215], v[84:87]
	v_mfma_f32_16x16x32_bf16 v[64:67], v[178:181], v[220:223], v[64:67]
	v_mfma_f32_16x16x32_bf16 v[80:83], v[188:191], v[220:223], v[80:83]
	v_mfma_f32_16x16x32_bf16 v[76:79], v[184:187], v[200:203], v[76:79]
	v_mfma_f32_16x16x32_bf16 v[92:95], v[192:195], v[200:203], v[92:95]
	v_mfma_f32_16x16x32_bf16 v[72:75], v[184:187], v[208:211], v[72:75]
	v_mfma_f32_16x16x32_bf16 v[88:91], v[192:195], v[208:211], v[88:91]
	v_mfma_f32_16x16x32_bf16 v[68:71], v[184:187], v[216:219], v[68:71]
	v_mfma_f32_16x16x32_bf16 v[84:87], v[192:195], v[216:219], v[84:87]
	v_mfma_f32_16x16x32_bf16 v[64:67], v[184:187], v[224:227], v[64:67]
	v_mfma_f32_16x16x32_bf16 v[80:83], v[192:195], v[224:227], v[80:83]
	s_barrier
; #define PG8_STAGE(bufoff, gbase, voff) do { _Pragma("unroll") for (int _i = 0; _i < 2; ++_i) \
;         __builtin_amdgcn_global_load_lds((const unsigned*)((const char*)(gbase) + (voff)[_i]), (PG8_LAS unsigned*)(lds + (bufoff) + ldsw + _i * 8192), 16, 0, 0); } while (0)
; #define PG8_LDA(dst, b, h) do { _Pragma("unroll") for (int m = 0; m < 4; ++m) _Pragma("unroll") for (int k = 0; k < 2; ++k) dst[m][k] = *(const PG8_LAS bf16x8*)(lds + PG8_SA(b, h) + aoff + m * 2048 + k * 1024); } while (0)
; #define PG8_MMA(ai, bj, At, Bt) do { __builtin_amdgcn_s_setprio(1); _Pragma("unroll") for (int m = 0; m < 4; ++m) _Pragma("unroll") for (int n = 0; n < 2; ++n) _Pragma("unroll") for (int k = 0; k < 2; ++k) \
;         acc[ai][bj][m][n] = __builtin_amdgcn_mfma_f32_16x16x32_bf16(Bt[n][k], At[m][k], acc[ai][bj][m][n], 0, 0, 0); __builtin_amdgcn_s_setprio(0); } while (0)
; #define PG8_WAIT_V(n) asm volatile("s_waitcnt vmcnt(" #n ")" ::: "memory")
; #define PG8_WAIT_L(n) asm volatile("s_waitcnt lgkmcnt(" #n ")" ::: "memory")
; #define PG8_BAR __builtin_amdgcn_s_barrier()
; #define PG8_SCHED __builtin_amdgcn_sched_barrier(0)
; template <class Epi, class Sched, bool ALIGN_EPI = false, bool SP2 = false>
; __device__ __forceinline__ void gemm_phase(PG8_LAS unsigned char* lds, const Gemm g, const Sched& S, const Epi& E) {
;     ...
;         for (int t = 0; t < nt; t += 2) {
;             const bool last = (t == nt - 2);
;     ...
;             PG8_LDA(At, 1, 1); PG8_STAGE(PG8_SB(1, 0), b3, voffB); PG8_STAGE(PG8_SB(1, 1), b3 + hstep, voffB); PG8_STAGE(PG8_SA(1, 0), a3, voffA);
;             PG8_WAIT_V(8); PG8_WAIT_L(0); PG8_BAR; PG8_MMA(1, 0, At, B0); PG8_MMA(1, 1, At, B1); PG8_BAR; PG8_SCHED;
	s_setprio 0
	s_add_i32 s36, s57, s33
	v_lshl_add_u64 v[148:149], v[148:149], 0, s[14:15]
	s_mov_b32 m0, s36
	ds_read_b128 v[196:199], v163 offset:49152
	ds_read_b128 v[200:203], v163 offset:50176
	ds_read_b128 v[204:207], v163 offset:51200
	ds_read_b128 v[208:211], v163 offset:52224
	ds_read_b128 v[212:215], v163 offset:53248
	ds_read_b128 v[216:219], v163 offset:54272
	ds_read_b128 v[220:223], v163 offset:55296
	ds_read_b128 v[224:227], v163 offset:56320
	global_load_lds_dwordx4 v[148:149], off
	s_add_i32 m0, s36, 0x2000
	s_add_u32 s34, s34, 0x100080
	v_lshl_add_u64 v[148:149], v[228:229], 0, s[14:15]
	s_addc_u32 s35, s35, 0
	s_add_i32 s36, s58, s33
	global_load_lds_dwordx4 v[148:149], off
	v_lshl_add_u64 v[148:149], s[34:35], 0, v[128:129]
	s_mov_b32 m0, s36
	s_nop 0
	global_load_lds_dwordx4 v[148:149], off
	v_lshl_add_u64 v[148:149], s[34:35], 0, v[130:131]
	s_add_i32 m0, s36, 0x2000
	s_nop 0
	global_load_lds_dwordx4 v[148:149], off
	v_lshl_add_u64 v[148:149], v[230:231], 0, s[14:15]
	s_mov_b32 m0, s41
	s_nop 0
	global_load_lds_dwordx4 v[148:149], off
	v_lshl_add_u64 v[148:149], v[232:233], 0, s[14:15]
	s_mov_b32 m0, s42
	s_nop 0
	global_load_lds_dwordx4 v[148:149], off
	s_waitcnt vmcnt(8)
	s_waitcnt lgkmcnt(0)
	s_setprio 1
	s_barrier
	v_mfma_f32_16x16x32_bf16 v[56:59], v[144:147], v[196:199], v[56:59]
	v_mfma_f32_16x16x32_bf16 v[60:63], v[170:173], v[196:199], v[60:63]
	v_mfma_f32_16x16x32_bf16 v[48:51], v[144:147], v[204:207], v[48:51]
	v_mfma_f32_16x16x32_bf16 v[52:55], v[170:173], v[204:207], v[52:55]
	v_mfma_f32_16x16x32_bf16 v[40:43], v[144:147], v[212:215], v[40:43]
	v_mfma_f32_16x16x32_bf16 v[44:47], v[170:173], v[212:215], v[44:47]
	v_mfma_f32_16x16x32_bf16 v[32:35], v[144:147], v[220:223], v[32:35]
	v_mfma_f32_16x16x32_bf16 v[36:39], v[170:173], v[220:223], v[36:39]
	v_mfma_f32_16x16x32_bf16 v[56:59], v[166:169], v[200:203], v[56:59]
	v_mfma_f32_16x16x32_bf16 v[60:63], v[174:177], v[200:203], v[60:63]
	v_mfma_f32_16x16x32_bf16 v[48:51], v[166:169], v[208:211], v[48:51]
	v_mfma_f32_16x16x32_bf16 v[52:55], v[174:177], v[208:211], v[52:55]
	v_mfma_f32_16x16x32_bf16 v[40:43], v[166:169], v[216:219], v[40:43]
	v_mfma_f32_16x16x32_bf16 v[44:47], v[174:177], v[216:219], v[44:47]
	v_mfma_f32_16x16x32_bf16 v[32:35], v[166:169], v[224:227], v[32:35]
	v_mfma_f32_16x16x32_bf16 v[36:39], v[174:177], v[224:227], v[36:39]
	s_setprio 0
	s_setprio 1
	v_mfma_f32_16x16x32_bf16 v[12:15], v[178:181], v[196:199], v[12:15]
	v_mfma_f32_16x16x32_bf16 v[28:31], v[188:191], v[196:199], v[28:31]
	v_mfma_f32_16x16x32_bf16 v[8:11], v[178:181], v[204:207], v[8:11]
	v_mfma_f32_16x16x32_bf16 v[24:27], v[188:191], v[204:207], v[24:27]
	v_mfma_f32_16x16x32_bf16 v[4:7], v[178:181], v[212:215], v[4:7]
	v_mfma_f32_16x16x32_bf16 v[20:23], v[188:191], v[212:215], v[20:23]
	v_mfma_f32_16x16x32_bf16 v[0:3], v[178:181], v[220:223], v[0:3]
	v_mfma_f32_16x16x32_bf16 v[16:19], v[188:191], v[220:223], v[16:19]
	v_mfma_f32_16x16x32_bf16 v[12:15], v[184:187], v[200:203], v[12:15]
	v_mfma_f32_16x16x32_bf16 v[28:31], v[192:195], v[200:203], v[28:31]
	v_mfma_f32_16x16x32_bf16 v[8:11], v[184:187], v[208:211], v[8:11]
	v_mfma_f32_16x16x32_bf16 v[24:27], v[192:195], v[208:211], v[24:27]
	v_mfma_f32_16x16x32_bf16 v[4:7], v[184:187], v[216:219], v[4:7]
	v_mfma_f32_16x16x32_bf16 v[20:23], v[192:195], v[216:219], v[20:23]
	v_mfma_f32_16x16x32_bf16 v[0:3], v[184:187], v[224:227], v[0:3]
	v_mfma_f32_16x16x32_bf16 v[16:19], v[192:195], v[224:227], v[16:19]
	s_barrier
	s_setprio 0
	s_add_i32 s56, s56, 2
	s_add_u32 s30, s30, 0x100
	s_addc_u32 s31, s31, 0
	s_add_u32 s54, s54, 0x100
	s_addc_u32 s55, s55, 0
	s_cmp_gt_u32 s56, 61
	s_cbranch_scc0 .LBB0_1343
	s_and_b64 vcc, exec, s[16:17]
	s_cbranch_vccz .LBB0_1346
	s_barrier
